# q/k RMS-norm + gain moved from the attention<false> unit loop into the in-proj GEMM epilogue (f32 accumulators, heads 8-23)
# speedup vs baseline: 1.0196x; 1.0072x over previous
; #define PG8_STAGE(bufoff, gbase, voff) do { _Pragma("unroll") for (int _i = 0; _i < 2; ++_i) \
;         __builtin_amdgcn_global_load_lds((const unsigned*)((const char*)(gbase) + (voff)[_i]), (PG8_LAS unsigned*)(lds + (bufoff) + ldsw + _i * 8192), 16, 0, 0); } while (0)
; template <class Epi, class Sched, bool ALIGN_EPI = false, bool SP2 = false>
; __device__ __forceinline__ void gemm_phase(PG8_LAS unsigned char* lds, const Gemm g, const Sched& S, const Epi& E) {
;     const int tid = threadIdx.x, wid = __builtin_amdgcn_readfirstlane(tid >> 6), lane = tid & 63, wr = wid >> 2, wc = wid & 3, fr = lane & 15, fq = lane >> 4;
;     const int K = g.K, nt = K / BK;
;     unsigned voffA[2], voffB[2];
; #pragma unroll
;     for (int i = 0; i < 2; ++i) { int R, C; stage_rc(tid * 16 + i * 8192, R, C); const int Rb = Epi::PERM2 ? (64 * (R >> 5) + perm32(R & 31)) : (Epi::PERM ? ((R & ~31) + perm32(R & 31)) : R);
;         voffA[i] = (unsigned)(R * K + C) * 2u; voffB[i] = (unsigned)(Rb * K + C) * 2u; }
;     const size_t kstep = (size_t)(BK * 2);
;     const size_t hstep = (size_t)HALF * K * 2;
;     const size_t hstepB = Epi::PERM2 ? (size_t)32 * K * 2 : hstep;
;     const size_t tstep = 2 * hstep;
;     const unsigned ldsw = (unsigned)wid * 1024u;
;     const int aoff = lds_byte(wr * 64 + fr, fq * 8), boff = lds_byte(wc * 32 + fr, fq * 8);
;     ...
;     Unit cur, nxt; int ui = 0;
;     if (!S.next(0, cur)) return;
;     f32x4 acc[2][2][4][2];
; #pragma unroll
;     for (int a = 0; a < 2; ++a)
; #pragma unroll
;         for (int b = 0; b < 2; ++b)
; #pragma unroll
;             for (int m = 0; m < 4; ++m)
; #pragma unroll
;                 for (int n = 0; n < 2; ++n) acc[a][b][m][n] = (f32x4){0.f, 0.f, 0.f, 0.f};
;     bf16x8 At[4][2], B0[2][2], B1[2][2];
;     const char* cA = (const char*)g.A + (size_t)cur.pm * tstep; const char* cB = (const char*)g.Bt + (size_t)cur.pn * tstep;
;     S.a_ready(cur);
;     if constexpr (SP2) {
;         PG8_STAGE(PG8_SB(0, 0), cB, voffB); PG8_STAGE(PG8_SB(0, 1), cB + hstepB, voffB); PG8_STAGE(PG8_SA(0, 0), cA, voffA); PG8_STAGE(PG8_SA(0, 1), cA + hstep, voffA);
;         if (wr == 1) PG8_BAR;
;         PG8_WAIT_V(2); PG8_BAR;
;         PG8_STAGE(PG8_SB(1, 0), cB + kstep, voffB); PG8_STAGE(PG8_SA(1, 0), cA + kstep, voffA); PG8_STAGE(PG8_SB(1, 1), cB + hstepB + kstep, voffB);
;         PG8_WAIT_V(6); PG8_BAR;
.LBB0_151:
	s_mov_b64 s[12:13], 0x80
	s_and_b32 s5, s0, 3
	s_add_i32 m0, s70, 0x18000
	v_lshl_add_u64 v[6:7], v[6:7], 0, s[12:13]
	s_lshl_b32 s74, s1, 6
	s_lshl_b32 s7, s1, 13
	s_lshl_b32 s14, s5, 12
	s_waitcnt vmcnt(2)
	s_barrier
	global_load_lds_dwordx4 v[6:7], off
	v_lshl_add_u64 v[4:5], v[4:5], 0, s[12:13]
	s_add_i32 m0, s70, 0x1a000
	s_add_i32 s75, s70, 0x8000
	s_add_i32 s76, s70, 0xa000
	global_load_lds_dwordx4 v[4:5], off
	v_lshl_add_u64 v[0:1], v[0:1], 0, s[12:13]
	s_mov_b32 m0, s75
	s_add_u32 s0, s58, 0x10080
	global_load_lds_dwordx4 v[0:1], off
	v_lshl_add_u64 v[0:1], v[2:3], 0, s[12:13]
	s_mov_b32 m0, s76
	s_addc_u32 s1, s59, 0
	global_load_lds_dwordx4 v[0:1], off
	s_add_i32 m0, s70, 0x1c000
	v_lshl_add_u64 v[0:1], s[0:1], 0, v[128:129]
	global_load_lds_dwordx4 v[0:1], off
	v_lshl_add_u64 v[0:1], s[0:1], 0, v[130:131]
	s_add_i32 m0, s70, 0x1e000
	v_lshlrev_b32_e32 v3, 2, v185
	global_load_lds_dwordx4 v[0:1], off
	v_lshrrev_b32_e32 v0, 1, v178
	v_and_b32_e32 v0, 24, v0
	v_lshlrev_b32_e32 v1, 1, v0
	v_lshl_or_b32 v2, v185, 6, v1
	v_or_b32_e32 v1, v1, v183
	v_bitop3_b32 v146, s14, v1, v184 bitop3:0xf6
	v_cvt_f32_u32_e32 v1, s68
	v_and_b32_e32 v3, 32, v3
	v_bitop3_b32 v2, v2, s7, v3 bitop3:0xde
	v_lshlrev_b32_e32 v3, 11, v181
	v_rcp_iflag_f32_e32 v1, v1
	s_cmpk_lt_u32 s8, 0x100
	s_cselect_b64 s[14:15], -1, 0
	s_lshl_b32 s77, s5, 19
	v_mul_f32_e32 v1, 0x4f7ffffe, v1
	v_cvt_u32_f32_e32 v1, v1
	s_lshl_b32 s78, s5, 6
	s_sub_i32 s5, 0, s68
	s_waitcnt vmcnt(6)
	v_readfirstlane_b32 s7, v1
	v_lshlrev_b32_e32 v1, 8, v178
	v_and_b32_e32 v1, 0x38000, v1
	v_or3_b32 v1, v179, v1, v3
	v_add_u32_e32 v134, v1, v180
	v_lshlrev_b32_e32 v1, 4, v182
	s_mul_i32 s5, s5, s7
	v_and_b32_e32 v1, 0x78000, v1
	v_or_b32_e32 v0, v184, v0
	s_mul_hi_u32 s5, s7, s5
	v_or3_b32 v1, v179, v1, v3
	s_add_i32 s88, 0, 0x10000
	s_add_i32 s89, 0, 0x14000
	v_and_b32_e32 v147, 7, v178
	v_cmp_gt_u32_e64 s[0:1], 8, v185
	s_mov_b32 s79, s54
	s_ashr_i32 s80, s2, 31
	s_add_i32 s81, s7, s5
	v_mov_b32_e32 v135, v133
	v_add_u32_e32 v136, v1, v180
	v_mov_b32_e32 v137, v133
	s_movk_i32 s87, 0x301
	v_add_u32_e32 v148, s88, v146
	v_add_u32_e32 v149, s89, v146
	v_add_u32_e32 v150, 0, v2
	v_lshlrev_b32_e32 v132, 1, v0
	v_mov_b64_e32 v[138:139], 0x17ff
	s_mov_b32 s90, 0
	s_barrier
	v_mbcnt_lo_u32_b32 v250, -1, 0
	v_mbcnt_hi_u32_b32 v250, -1, v250
	v_lshrrev_b32_e32 v250, 4, v250
	v_lshlrev_b32_e32 v250, 5, v250
	s_lshl_b32 s100, s78, 2
	v_add_u32_e32 v250, s100, v250
	s_branch .LBB0_154

;     __device__ __forceinline__ void operator()(const pg8::f32x4 (&acc)[2][2][4][2], const pg8::Unit& u, int wr, int wc, int fr, int fq) const {
;         const int pn = u.pn; const int hi8 = (fr >> 3) & 1, fr7 = fr & 7; const int rbase = u.pm * 256 + wr * 64 + fr7;
;         const bool qkv = (pn >= 4 && pn < 22);
;         const bool act = !qkv && pn >= 2;
;         const int ld = pn < 2 ? 512 : 1024;
;         bf16_t* base; int dsh = 0; size_t rowstride_tok = 0; int ecol;
;         if (qkv) { const int which = (pn - 4) / 6, ct = (pn - 4) % 6; dsh = 2 * (ct >> 1);
;             base = Q + (size_t)which * ((WS_K - WS_Q) / 2) + (size_t)(ct * 4 + wc) * SEQ * 64; ecol = 32 * hi8 + 8 * fq; }
;         else { const int c0 = pn < 2 ? pn * 256 : (pn < 4 ? (pn - 2) * 256 : 512 + (pn - 22) * 256); base = (pn < 2 ? Z : G) + c0 + wc * 64; ecol = 32 * hi8 + 8 * fq; }
;         const int dmask = (1 << dsh) - 1, Lc = SEQ >> dsh;
.LBB0_154:
	s_mov_b32 s100, 0
	s_add_i32 s101, s4, -4
	s_cmp_lt_u32 s101, 12
	s_cbranch_scc0 .Lp1_gdone
	s_cmp_lt_u32 s101, 6
	s_cselect_b32 vcc_lo, s42, s44
	s_cselect_b32 vcc_hi, s43, s45
	s_cselect_b32 s100, 0, 6
	s_sub_i32 s101, s101, s100
	s_cmp_eq_u32 s100, 0
	s_cselect_b32 s100, 0x3e38aa3b, 1.0
	s_cmp_lt_u32 s101, 2
	s_cbranch_scc1 .Lp1_gskip
	s_lshl_b32 s101, s101, 10
	s_add_u32 vcc_lo, vcc_lo, s101
	s_addc_u32 vcc_hi, vcc_hi, 0
	s_mov_b32 s101, s100
	s_mov_b32 s100, 1
	global_load_dwordx4 v[234:237], v250, vcc
	global_load_dwordx4 v[238:241], v250, vcc offset:16
	global_load_dwordx4 v[242:245], v250, vcc offset:128
	global_load_dwordx4 v[246:249], v250, vcc offset:144
	s_branch .Lp1_gdone
.Lp1_gskip:
	s_mov_b32 s100, 0

; __device__ __forceinline__ unsigned pk2(float lo, float hi) { f32x2_t v = {lo, hi}; bf16x2_t b = __builtin_convertvector(v, bf16x2_t); return __builtin_bit_cast(unsigned, b); }
; __device__ __forceinline__ float silu_f(float v) { return v * __builtin_amdgcn_rcpf(1.f + __builtin_amdgcn_exp2f(-v * LOG2E)); }
;     __device__ __forceinline__ void operator()(const pg8::f32x4 (&acc)[2][2][4][2], const pg8::Unit& u, int wr, int wc, int fr, int fq) const {
;     ...
;             for (int m = 0; m < 4; ++m) {
;                 pg8::f32x4 a0 = acc[ai][0][m][0], a1 = acc[ai][0][m][1], b0 = acc[ai][1][m][0], b1 = acc[ai][1][m][1];
;                 if (act) {
; #pragma unroll
;                     for (int e = 0; e < 4; ++e) { a0[e] = silu_f(a0[e]); a1[e] = silu_f(a1[e]); b0[e] = silu_f(b0[e]); b1[e] = silu_f(b1[e]); } }
;                 u32x4 A, B; A.x = pk2(a0[0], a0[1]); A.y = pk2(a0[2], a0[3]); A.z = pk2(a1[0], a1[1]); A.w = pk2(a1[2], a1[3]);
;                 B.x = pk2(b0[0], b0[1]); B.y = pk2(b0[2], b0[3]); B.z = pk2(b1[0], b1[1]); B.w = pk2(b1[2], b1[3]);
; template <bool FUSED> __device__ __forceinline__ void attn_phase(const Args& a, LAS unsigned char* lds, int tid, int lane, int wave) {
;     ...
;             float ss = 0.f;
; #pragma unroll
;             for (int ks = 0; ks < 4; ++ks)
; #pragma unroll
;                 for (int e = 0; e < 4; ++e) { const float lo = bflo(qv[ks][e]), hi = bfhi(qv[ks][e]); ss += lo * lo + hi * hi; }
;             ss += __shfl_xor(ss, 32);
;             const float rq = 0.125f * LOG2E * __builtin_amdgcn_rsqf(ss * (1.f / 64.f) + 1e-6f);
; #pragma unroll
;             for (int ks = 0; ks < 4; ++ks) { const f32x4 g0 = *(const f32x4*)(a.qw + hd * 64 + 16 * ks + 8 * h), g1 = *(const f32x4*)(a.qw + hd * 64 + 16 * ks + 8 * h + 4); u32x4 wv;
;                 wv.x = pk2(bflo(qv[ks].x) * rq * g0.x, bfhi(qv[ks].x) * rq * g0.y); wv.y = pk2(bflo(qv[ks].y) * rq * g0.z, bfhi(qv[ks].y) * rq * g0.w);
;                 wv.z = pk2(bflo(qv[ks].z) * rq * g1.x, bfhi(qv[ks].z) * rq * g1.y); wv.w = pk2(bflo(qv[ks].w) * rq * g1.z, bfhi(qv[ks].w) * rq * g1.w);
;                 qf[ks] = __builtin_bit_cast(bf16x8, wv); }
.LBB0_175:
	s_cmp_eq_u32 s100, 0
	s_cbranch_scc1 .Lp1_nn0
	v_pk_mul_f32 v[156:157], v[124:125], v[124:125]
	v_pk_mul_f32 v[158:159], v[126:127], v[126:127]
	v_pk_fma_f32 v[156:157], v[120:121], v[120:121], v[156:157]
	v_pk_fma_f32 v[158:159], v[122:123], v[122:123], v[158:159]
	v_pk_fma_f32 v[156:157], v[116:117], v[116:117], v[156:157]
	v_pk_fma_f32 v[158:159], v[118:119], v[118:119], v[158:159]
	v_pk_fma_f32 v[156:157], v[112:113], v[112:113], v[156:157]
	v_pk_fma_f32 v[158:159], v[114:115], v[114:115], v[158:159]
	v_pk_add_f32 v[156:157], v[156:157], v[158:159]
	v_add_f32_e32 v156, v156, v157
	v_mov_b32_e32 v157, v156
	s_nop 1
	v_permlane16_swap_b32_e32 v156, v157
	v_add_f32_e32 v156, v156, v157
	v_mov_b32_e32 v157, v156
	s_nop 1
	v_permlane32_swap_b32_e32 v156, v157
	v_add_f32_e32 v156, v156, v157
	v_mul_f32_e32 v156, 0x3c800000, v156
	v_add_f32_e32 v156, 0x358637bd, v156
	v_rsq_f32_e32 v156, v156
	s_nop 0
	v_mul_f32_e32 v156, s101, v156
	v_pk_mul_f32 v[124:125], v[124:125], v[156:157] op_sel_hi:[1,0]
	v_pk_mul_f32 v[126:127], v[126:127], v[156:157] op_sel_hi:[1,0]
	v_pk_mul_f32 v[120:121], v[120:121], v[156:157] op_sel_hi:[1,0]
	v_pk_mul_f32 v[122:123], v[122:123], v[156:157] op_sel_hi:[1,0]
	v_pk_mul_f32 v[116:117], v[116:117], v[156:157] op_sel_hi:[1,0]
	v_pk_mul_f32 v[118:119], v[118:119], v[156:157] op_sel_hi:[1,0]
	v_pk_mul_f32 v[112:113], v[112:113], v[156:157] op_sel_hi:[1,0]
	v_pk_mul_f32 v[114:115], v[114:115], v[156:157] op_sel_hi:[1,0]
	v_pk_mul_f32 v[124:125], v[124:125], v[234:235]
	v_pk_mul_f32 v[126:127], v[126:127], v[236:237]
	v_pk_mul_f32 v[120:121], v[120:121], v[238:239]
	v_pk_mul_f32 v[122:123], v[122:123], v[240:241]
	v_pk_mul_f32 v[116:117], v[116:117], v[242:243]
	v_pk_mul_f32 v[118:119], v[118:119], v[244:245]
	v_pk_mul_f32 v[112:113], v[112:113], v[246:247]
	v_pk_mul_f32 v[114:115], v[114:115], v[248:249]

; __device__ __forceinline__ unsigned pk2(float lo, float hi) { f32x2_t v = {lo, hi}; bf16x2_t b = __builtin_convertvector(v, bf16x2_t); return __builtin_bit_cast(unsigned, b); }
; __device__ __forceinline__ float silu_f(float v) { return v * __builtin_amdgcn_rcpf(1.f + __builtin_amdgcn_exp2f(-v * LOG2E)); }
;     __device__ __forceinline__ void operator()(const pg8::f32x4 (&acc)[2][2][4][2], const pg8::Unit& u, int wr, int wc, int fr, int fq) const {
;     ...
;             for (int m = 0; m < 4; ++m) {
;                 pg8::f32x4 a0 = acc[ai][0][m][0], a1 = acc[ai][0][m][1], b0 = acc[ai][1][m][0], b1 = acc[ai][1][m][1];
;                 if (act) {
; #pragma unroll
;                     for (int e = 0; e < 4; ++e) { a0[e] = silu_f(a0[e]); a1[e] = silu_f(a1[e]); b0[e] = silu_f(b0[e]); b1[e] = silu_f(b1[e]); } }
;                 u32x4 A, B; A.x = pk2(a0[0], a0[1]); A.y = pk2(a0[2], a0[3]); A.z = pk2(a1[0], a1[1]); A.w = pk2(a1[2], a1[3]);
;                 B.x = pk2(b0[0], b0[1]); B.y = pk2(b0[2], b0[3]); B.z = pk2(b1[0], b1[1]); B.w = pk2(b1[2], b1[3]);
; template <bool FUSED> __device__ __forceinline__ void attn_phase(const Args& a, LAS unsigned char* lds, int tid, int lane, int wave) {
;     ...
;             float ss = 0.f;
; #pragma unroll
;             for (int ks = 0; ks < 4; ++ks)
; #pragma unroll
;                 for (int e = 0; e < 4; ++e) { const float lo = bflo(qv[ks][e]), hi = bfhi(qv[ks][e]); ss += lo * lo + hi * hi; }
;             ss += __shfl_xor(ss, 32);
;             const float rq = 0.125f * LOG2E * __builtin_amdgcn_rsqf(ss * (1.f / 64.f) + 1e-6f);
; #pragma unroll
;             for (int ks = 0; ks < 4; ++ks) { const f32x4 g0 = *(const f32x4*)(a.qw + hd * 64 + 16 * ks + 8 * h), g1 = *(const f32x4*)(a.qw + hd * 64 + 16 * ks + 8 * h + 4); u32x4 wv;
;                 wv.x = pk2(bflo(qv[ks].x) * rq * g0.x, bfhi(qv[ks].x) * rq * g0.y); wv.y = pk2(bflo(qv[ks].y) * rq * g0.z, bfhi(qv[ks].y) * rq * g0.w);
;                 wv.z = pk2(bflo(qv[ks].z) * rq * g1.x, bfhi(qv[ks].z) * rq * g1.y); wv.w = pk2(bflo(qv[ks].w) * rq * g1.z, bfhi(qv[ks].w) * rq * g1.w);
;                 qf[ks] = __builtin_bit_cast(bf16x8, wv); }
.LBB0_179:
	s_cmp_eq_u32 s100, 0
	s_cbranch_scc1 .Lp1_nn1
	v_pk_mul_f32 v[156:157], v[108:109], v[108:109]
	v_pk_mul_f32 v[158:159], v[110:111], v[110:111]
	v_pk_fma_f32 v[156:157], v[104:105], v[104:105], v[156:157]
	v_pk_fma_f32 v[158:159], v[106:107], v[106:107], v[158:159]
	v_pk_fma_f32 v[156:157], v[100:101], v[100:101], v[156:157]
	v_pk_fma_f32 v[158:159], v[102:103], v[102:103], v[158:159]
	v_pk_fma_f32 v[156:157], v[96:97], v[96:97], v[156:157]
	v_pk_fma_f32 v[158:159], v[98:99], v[98:99], v[158:159]
	v_pk_add_f32 v[156:157], v[156:157], v[158:159]
	v_add_f32_e32 v156, v156, v157
	v_mov_b32_e32 v157, v156
	s_nop 1
	v_permlane16_swap_b32_e32 v156, v157
	v_add_f32_e32 v156, v156, v157
	v_mov_b32_e32 v157, v156
	s_nop 1
	v_permlane32_swap_b32_e32 v156, v157
	v_add_f32_e32 v156, v156, v157
	v_mul_f32_e32 v156, 0x3c800000, v156
	v_add_f32_e32 v156, 0x358637bd, v156
	v_rsq_f32_e32 v156, v156
	s_nop 0
	v_mul_f32_e32 v156, s101, v156
	v_pk_mul_f32 v[108:109], v[108:109], v[156:157] op_sel_hi:[1,0]
	v_pk_mul_f32 v[110:111], v[110:111], v[156:157] op_sel_hi:[1,0]
	v_pk_mul_f32 v[104:105], v[104:105], v[156:157] op_sel_hi:[1,0]
	v_pk_mul_f32 v[106:107], v[106:107], v[156:157] op_sel_hi:[1,0]
	v_pk_mul_f32 v[100:101], v[100:101], v[156:157] op_sel_hi:[1,0]
	v_pk_mul_f32 v[102:103], v[102:103], v[156:157] op_sel_hi:[1,0]
	v_pk_mul_f32 v[96:97], v[96:97], v[156:157] op_sel_hi:[1,0]
	v_pk_mul_f32 v[98:99], v[98:99], v[156:157] op_sel_hi:[1,0]
	v_pk_mul_f32 v[108:109], v[108:109], v[234:235]
	v_pk_mul_f32 v[110:111], v[110:111], v[236:237]
	v_pk_mul_f32 v[104:105], v[104:105], v[238:239]
	v_pk_mul_f32 v[106:107], v[106:107], v[240:241]
	v_pk_mul_f32 v[100:101], v[100:101], v[242:243]
	v_pk_mul_f32 v[102:103], v[102:103], v[244:245]
	v_pk_mul_f32 v[96:97], v[96:97], v[246:247]
	v_pk_mul_f32 v[98:99], v[98:99], v[248:249]

; __device__ __forceinline__ unsigned pk2(float lo, float hi) { f32x2_t v = {lo, hi}; bf16x2_t b = __builtin_convertvector(v, bf16x2_t); return __builtin_bit_cast(unsigned, b); }
; __device__ __forceinline__ float silu_f(float v) { return v * __builtin_amdgcn_rcpf(1.f + __builtin_amdgcn_exp2f(-v * LOG2E)); }
;     __device__ __forceinline__ void operator()(const pg8::f32x4 (&acc)[2][2][4][2], const pg8::Unit& u, int wr, int wc, int fr, int fq) const {
;     ...
;             for (int m = 0; m < 4; ++m) {
;                 pg8::f32x4 a0 = acc[ai][0][m][0], a1 = acc[ai][0][m][1], b0 = acc[ai][1][m][0], b1 = acc[ai][1][m][1];
;                 if (act) {
; #pragma unroll
;                     for (int e = 0; e < 4; ++e) { a0[e] = silu_f(a0[e]); a1[e] = silu_f(a1[e]); b0[e] = silu_f(b0[e]); b1[e] = silu_f(b1[e]); } }
;                 u32x4 A, B; A.x = pk2(a0[0], a0[1]); A.y = pk2(a0[2], a0[3]); A.z = pk2(a1[0], a1[1]); A.w = pk2(a1[2], a1[3]);
;                 B.x = pk2(b0[0], b0[1]); B.y = pk2(b0[2], b0[3]); B.z = pk2(b1[0], b1[1]); B.w = pk2(b1[2], b1[3]);
; template <bool FUSED> __device__ __forceinline__ void attn_phase(const Args& a, LAS unsigned char* lds, int tid, int lane, int wave) {
;     ...
;             float ss = 0.f;
; #pragma unroll
;             for (int ks = 0; ks < 4; ++ks)
; #pragma unroll
;                 for (int e = 0; e < 4; ++e) { const float lo = bflo(qv[ks][e]), hi = bfhi(qv[ks][e]); ss += lo * lo + hi * hi; }
;             ss += __shfl_xor(ss, 32);
;             const float rq = 0.125f * LOG2E * __builtin_amdgcn_rsqf(ss * (1.f / 64.f) + 1e-6f);
; #pragma unroll
;             for (int ks = 0; ks < 4; ++ks) { const f32x4 g0 = *(const f32x4*)(a.qw + hd * 64 + 16 * ks + 8 * h), g1 = *(const f32x4*)(a.qw + hd * 64 + 16 * ks + 8 * h + 4); u32x4 wv;
;                 wv.x = pk2(bflo(qv[ks].x) * rq * g0.x, bfhi(qv[ks].x) * rq * g0.y); wv.y = pk2(bflo(qv[ks].y) * rq * g0.z, bfhi(qv[ks].y) * rq * g0.w);
;                 wv.z = pk2(bflo(qv[ks].z) * rq * g1.x, bfhi(qv[ks].z) * rq * g1.y); wv.w = pk2(bflo(qv[ks].w) * rq * g1.z, bfhi(qv[ks].w) * rq * g1.w);
;                 qf[ks] = __builtin_bit_cast(bf16x8, wv); }
.LBB0_183:
	s_cmp_eq_u32 s100, 0
	s_cbranch_scc1 .Lp1_nn2
	v_pk_mul_f32 v[156:157], v[92:93], v[92:93]
	v_pk_mul_f32 v[158:159], v[94:95], v[94:95]
	v_pk_fma_f32 v[156:157], v[88:89], v[88:89], v[156:157]
	v_pk_fma_f32 v[158:159], v[90:91], v[90:91], v[158:159]
	v_pk_fma_f32 v[156:157], v[84:85], v[84:85], v[156:157]
	v_pk_fma_f32 v[158:159], v[86:87], v[86:87], v[158:159]
	v_pk_fma_f32 v[156:157], v[80:81], v[80:81], v[156:157]
	v_pk_fma_f32 v[158:159], v[82:83], v[82:83], v[158:159]
	v_pk_add_f32 v[156:157], v[156:157], v[158:159]
	v_add_f32_e32 v156, v156, v157
	v_mov_b32_e32 v157, v156
	s_nop 1
	v_permlane16_swap_b32_e32 v156, v157
	v_add_f32_e32 v156, v156, v157
	v_mov_b32_e32 v157, v156
	s_nop 1
	v_permlane32_swap_b32_e32 v156, v157
	v_add_f32_e32 v156, v156, v157
	v_mul_f32_e32 v156, 0x3c800000, v156
	v_add_f32_e32 v156, 0x358637bd, v156
	v_rsq_f32_e32 v156, v156
	s_nop 0
	v_mul_f32_e32 v156, s101, v156
	v_pk_mul_f32 v[92:93], v[92:93], v[156:157] op_sel_hi:[1,0]
	v_pk_mul_f32 v[94:95], v[94:95], v[156:157] op_sel_hi:[1,0]
	v_pk_mul_f32 v[88:89], v[88:89], v[156:157] op_sel_hi:[1,0]
	v_pk_mul_f32 v[90:91], v[90:91], v[156:157] op_sel_hi:[1,0]
	v_pk_mul_f32 v[84:85], v[84:85], v[156:157] op_sel_hi:[1,0]
	v_pk_mul_f32 v[86:87], v[86:87], v[156:157] op_sel_hi:[1,0]
	v_pk_mul_f32 v[80:81], v[80:81], v[156:157] op_sel_hi:[1,0]
	v_pk_mul_f32 v[82:83], v[82:83], v[156:157] op_sel_hi:[1,0]
	v_pk_mul_f32 v[92:93], v[92:93], v[234:235]
	v_pk_mul_f32 v[94:95], v[94:95], v[236:237]
	v_pk_mul_f32 v[88:89], v[88:89], v[238:239]
	v_pk_mul_f32 v[90:91], v[90:91], v[240:241]
	v_pk_mul_f32 v[84:85], v[84:85], v[242:243]
	v_pk_mul_f32 v[86:87], v[86:87], v[244:245]
	v_pk_mul_f32 v[80:81], v[80:81], v[246:247]
	v_pk_mul_f32 v[82:83], v[82:83], v[248:249]

; __device__ __forceinline__ unsigned pk2(float lo, float hi) { f32x2_t v = {lo, hi}; bf16x2_t b = __builtin_convertvector(v, bf16x2_t); return __builtin_bit_cast(unsigned, b); }
; __device__ __forceinline__ float silu_f(float v) { return v * __builtin_amdgcn_rcpf(1.f + __builtin_amdgcn_exp2f(-v * LOG2E)); }
;     __device__ __forceinline__ void operator()(const pg8::f32x4 (&acc)[2][2][4][2], const pg8::Unit& u, int wr, int wc, int fr, int fq) const {
;     ...
;             for (int m = 0; m < 4; ++m) {
;                 pg8::f32x4 a0 = acc[ai][0][m][0], a1 = acc[ai][0][m][1], b0 = acc[ai][1][m][0], b1 = acc[ai][1][m][1];
;                 if (act) {
; #pragma unroll
;                     for (int e = 0; e < 4; ++e) { a0[e] = silu_f(a0[e]); a1[e] = silu_f(a1[e]); b0[e] = silu_f(b0[e]); b1[e] = silu_f(b1[e]); } }
;                 u32x4 A, B; A.x = pk2(a0[0], a0[1]); A.y = pk2(a0[2], a0[3]); A.z = pk2(a1[0], a1[1]); A.w = pk2(a1[2], a1[3]);
;                 B.x = pk2(b0[0], b0[1]); B.y = pk2(b0[2], b0[3]); B.z = pk2(b1[0], b1[1]); B.w = pk2(b1[2], b1[3]);
; template <bool FUSED> __device__ __forceinline__ void attn_phase(const Args& a, LAS unsigned char* lds, int tid, int lane, int wave) {
;     ...
;             float ss = 0.f;
; #pragma unroll
;             for (int ks = 0; ks < 4; ++ks)
; #pragma unroll
;                 for (int e = 0; e < 4; ++e) { const float lo = bflo(qv[ks][e]), hi = bfhi(qv[ks][e]); ss += lo * lo + hi * hi; }
;             ss += __shfl_xor(ss, 32);
;             const float rq = 0.125f * LOG2E * __builtin_amdgcn_rsqf(ss * (1.f / 64.f) + 1e-6f);
; #pragma unroll
;             for (int ks = 0; ks < 4; ++ks) { const f32x4 g0 = *(const f32x4*)(a.qw + hd * 64 + 16 * ks + 8 * h), g1 = *(const f32x4*)(a.qw + hd * 64 + 16 * ks + 8 * h + 4); u32x4 wv;
;                 wv.x = pk2(bflo(qv[ks].x) * rq * g0.x, bfhi(qv[ks].x) * rq * g0.y); wv.y = pk2(bflo(qv[ks].y) * rq * g0.z, bfhi(qv[ks].y) * rq * g0.w);
;                 wv.z = pk2(bflo(qv[ks].z) * rq * g1.x, bfhi(qv[ks].z) * rq * g1.y); wv.w = pk2(bflo(qv[ks].w) * rq * g1.z, bfhi(qv[ks].w) * rq * g1.w);
;                 qf[ks] = __builtin_bit_cast(bf16x8, wv); }
.LBB0_187:
	s_cmp_eq_u32 s100, 0
	s_cbranch_scc1 .Lp1_nn3
	v_pk_mul_f32 v[156:157], v[76:77], v[76:77]
	v_pk_mul_f32 v[158:159], v[78:79], v[78:79]
	v_pk_fma_f32 v[156:157], v[72:73], v[72:73], v[156:157]
	v_pk_fma_f32 v[158:159], v[74:75], v[74:75], v[158:159]
	v_pk_fma_f32 v[156:157], v[68:69], v[68:69], v[156:157]
	v_pk_fma_f32 v[158:159], v[70:71], v[70:71], v[158:159]
	v_pk_fma_f32 v[156:157], v[64:65], v[64:65], v[156:157]
	v_pk_fma_f32 v[158:159], v[66:67], v[66:67], v[158:159]
	v_pk_add_f32 v[156:157], v[156:157], v[158:159]
	v_add_f32_e32 v156, v156, v157
	v_mov_b32_e32 v157, v156
	s_nop 1
	v_permlane16_swap_b32_e32 v156, v157
	v_add_f32_e32 v156, v156, v157
	v_mov_b32_e32 v157, v156
	s_nop 1
	v_permlane32_swap_b32_e32 v156, v157
	v_add_f32_e32 v156, v156, v157
	v_mul_f32_e32 v156, 0x3c800000, v156
	v_add_f32_e32 v156, 0x358637bd, v156
	v_rsq_f32_e32 v156, v156
	s_nop 0
	v_mul_f32_e32 v156, s101, v156
	v_pk_mul_f32 v[76:77], v[76:77], v[156:157] op_sel_hi:[1,0]
	v_pk_mul_f32 v[78:79], v[78:79], v[156:157] op_sel_hi:[1,0]
	v_pk_mul_f32 v[72:73], v[72:73], v[156:157] op_sel_hi:[1,0]
	v_pk_mul_f32 v[74:75], v[74:75], v[156:157] op_sel_hi:[1,0]
	v_pk_mul_f32 v[68:69], v[68:69], v[156:157] op_sel_hi:[1,0]
	v_pk_mul_f32 v[70:71], v[70:71], v[156:157] op_sel_hi:[1,0]
	v_pk_mul_f32 v[64:65], v[64:65], v[156:157] op_sel_hi:[1,0]
	v_pk_mul_f32 v[66:67], v[66:67], v[156:157] op_sel_hi:[1,0]
	v_pk_mul_f32 v[76:77], v[76:77], v[234:235]
	v_pk_mul_f32 v[78:79], v[78:79], v[236:237]
	v_pk_mul_f32 v[72:73], v[72:73], v[238:239]
	v_pk_mul_f32 v[74:75], v[74:75], v[240:241]
	v_pk_mul_f32 v[68:69], v[68:69], v[242:243]
	v_pk_mul_f32 v[70:71], v[70:71], v[244:245]
	v_pk_mul_f32 v[64:65], v[64:65], v[246:247]
	v_pk_mul_f32 v[66:67], v[66:67], v[248:249]

; __device__ __forceinline__ unsigned pk2(float lo, float hi) { f32x2_t v = {lo, hi}; bf16x2_t b = __builtin_convertvector(v, bf16x2_t); return __builtin_bit_cast(unsigned, b); }
; __device__ __forceinline__ float silu_f(float v) { return v * __builtin_amdgcn_rcpf(1.f + __builtin_amdgcn_exp2f(-v * LOG2E)); }
;     __device__ __forceinline__ void operator()(const pg8::f32x4 (&acc)[2][2][4][2], const pg8::Unit& u, int wr, int wc, int fr, int fq) const {
;     ...
;             for (int m = 0; m < 4; ++m) {
;                 pg8::f32x4 a0 = acc[ai][0][m][0], a1 = acc[ai][0][m][1], b0 = acc[ai][1][m][0], b1 = acc[ai][1][m][1];
;                 if (act) {
; #pragma unroll
;                     for (int e = 0; e < 4; ++e) { a0[e] = silu_f(a0[e]); a1[e] = silu_f(a1[e]); b0[e] = silu_f(b0[e]); b1[e] = silu_f(b1[e]); } }
;                 u32x4 A, B; A.x = pk2(a0[0], a0[1]); A.y = pk2(a0[2], a0[3]); A.z = pk2(a1[0], a1[1]); A.w = pk2(a1[2], a1[3]);
;                 B.x = pk2(b0[0], b0[1]); B.y = pk2(b0[2], b0[3]); B.z = pk2(b1[0], b1[1]); B.w = pk2(b1[2], b1[3]);
; template <bool FUSED> __device__ __forceinline__ void attn_phase(const Args& a, LAS unsigned char* lds, int tid, int lane, int wave) {
;     ...
;             float ss = 0.f;
; #pragma unroll
;             for (int ks = 0; ks < 4; ++ks)
; #pragma unroll
;                 for (int e = 0; e < 4; ++e) { const float lo = bflo(qv[ks][e]), hi = bfhi(qv[ks][e]); ss += lo * lo + hi * hi; }
;             ss += __shfl_xor(ss, 32);
;             const float rq = 0.125f * LOG2E * __builtin_amdgcn_rsqf(ss * (1.f / 64.f) + 1e-6f);
; #pragma unroll
;             for (int ks = 0; ks < 4; ++ks) { const f32x4 g0 = *(const f32x4*)(a.qw + hd * 64 + 16 * ks + 8 * h), g1 = *(const f32x4*)(a.qw + hd * 64 + 16 * ks + 8 * h + 4); u32x4 wv;
;                 wv.x = pk2(bflo(qv[ks].x) * rq * g0.x, bfhi(qv[ks].x) * rq * g0.y); wv.y = pk2(bflo(qv[ks].y) * rq * g0.z, bfhi(qv[ks].y) * rq * g0.w);
;                 wv.z = pk2(bflo(qv[ks].z) * rq * g1.x, bfhi(qv[ks].z) * rq * g1.y); wv.w = pk2(bflo(qv[ks].w) * rq * g1.z, bfhi(qv[ks].w) * rq * g1.w);
;                 qf[ks] = __builtin_bit_cast(bf16x8, wv); }
.LBB0_191:
	s_cmp_eq_u32 s100, 0
	s_cbranch_scc1 .Lp1_nn4
	v_pk_mul_f32 v[156:157], v[60:61], v[60:61]
	v_pk_mul_f32 v[158:159], v[62:63], v[62:63]
	v_pk_fma_f32 v[156:157], v[56:57], v[56:57], v[156:157]
	v_pk_fma_f32 v[158:159], v[58:59], v[58:59], v[158:159]
	v_pk_fma_f32 v[156:157], v[52:53], v[52:53], v[156:157]
	v_pk_fma_f32 v[158:159], v[54:55], v[54:55], v[158:159]
	v_pk_fma_f32 v[156:157], v[48:49], v[48:49], v[156:157]
	v_pk_fma_f32 v[158:159], v[50:51], v[50:51], v[158:159]
	v_pk_add_f32 v[156:157], v[156:157], v[158:159]
	v_add_f32_e32 v156, v156, v157
	v_mov_b32_e32 v157, v156
	s_nop 1
	v_permlane16_swap_b32_e32 v156, v157
	v_add_f32_e32 v156, v156, v157
	v_mov_b32_e32 v157, v156
	s_nop 1
	v_permlane32_swap_b32_e32 v156, v157
	v_add_f32_e32 v156, v156, v157
	v_mul_f32_e32 v156, 0x3c800000, v156
	v_add_f32_e32 v156, 0x358637bd, v156
	v_rsq_f32_e32 v156, v156
	s_nop 0
	v_mul_f32_e32 v156, s101, v156
	v_pk_mul_f32 v[60:61], v[60:61], v[156:157] op_sel_hi:[1,0]
	v_pk_mul_f32 v[62:63], v[62:63], v[156:157] op_sel_hi:[1,0]
	v_pk_mul_f32 v[56:57], v[56:57], v[156:157] op_sel_hi:[1,0]
	v_pk_mul_f32 v[58:59], v[58:59], v[156:157] op_sel_hi:[1,0]
	v_pk_mul_f32 v[52:53], v[52:53], v[156:157] op_sel_hi:[1,0]
	v_pk_mul_f32 v[54:55], v[54:55], v[156:157] op_sel_hi:[1,0]
	v_pk_mul_f32 v[48:49], v[48:49], v[156:157] op_sel_hi:[1,0]
	v_pk_mul_f32 v[50:51], v[50:51], v[156:157] op_sel_hi:[1,0]
	v_pk_mul_f32 v[60:61], v[60:61], v[234:235]
	v_pk_mul_f32 v[62:63], v[62:63], v[236:237]
	v_pk_mul_f32 v[56:57], v[56:57], v[238:239]
	v_pk_mul_f32 v[58:59], v[58:59], v[240:241]
	v_pk_mul_f32 v[52:53], v[52:53], v[242:243]
	v_pk_mul_f32 v[54:55], v[54:55], v[244:245]
	v_pk_mul_f32 v[48:49], v[48:49], v[246:247]
	v_pk_mul_f32 v[50:51], v[50:51], v[248:249]

; __device__ __forceinline__ unsigned pk2(float lo, float hi) { f32x2_t v = {lo, hi}; bf16x2_t b = __builtin_convertvector(v, bf16x2_t); return __builtin_bit_cast(unsigned, b); }
; __device__ __forceinline__ float silu_f(float v) { return v * __builtin_amdgcn_rcpf(1.f + __builtin_amdgcn_exp2f(-v * LOG2E)); }
;     __device__ __forceinline__ void operator()(const pg8::f32x4 (&acc)[2][2][4][2], const pg8::Unit& u, int wr, int wc, int fr, int fq) const {
;     ...
;             for (int m = 0; m < 4; ++m) {
;                 pg8::f32x4 a0 = acc[ai][0][m][0], a1 = acc[ai][0][m][1], b0 = acc[ai][1][m][0], b1 = acc[ai][1][m][1];
;                 if (act) {
; #pragma unroll
;                     for (int e = 0; e < 4; ++e) { a0[e] = silu_f(a0[e]); a1[e] = silu_f(a1[e]); b0[e] = silu_f(b0[e]); b1[e] = silu_f(b1[e]); } }
;                 u32x4 A, B; A.x = pk2(a0[0], a0[1]); A.y = pk2(a0[2], a0[3]); A.z = pk2(a1[0], a1[1]); A.w = pk2(a1[2], a1[3]);
;                 B.x = pk2(b0[0], b0[1]); B.y = pk2(b0[2], b0[3]); B.z = pk2(b1[0], b1[1]); B.w = pk2(b1[2], b1[3]);
; template <bool FUSED> __device__ __forceinline__ void attn_phase(const Args& a, LAS unsigned char* lds, int tid, int lane, int wave) {
;     ...
;             float ss = 0.f;
; #pragma unroll
;             for (int ks = 0; ks < 4; ++ks)
; #pragma unroll
;                 for (int e = 0; e < 4; ++e) { const float lo = bflo(qv[ks][e]), hi = bfhi(qv[ks][e]); ss += lo * lo + hi * hi; }
;             ss += __shfl_xor(ss, 32);
;             const float rq = 0.125f * LOG2E * __builtin_amdgcn_rsqf(ss * (1.f / 64.f) + 1e-6f);
; #pragma unroll
;             for (int ks = 0; ks < 4; ++ks) { const f32x4 g0 = *(const f32x4*)(a.qw + hd * 64 + 16 * ks + 8 * h), g1 = *(const f32x4*)(a.qw + hd * 64 + 16 * ks + 8 * h + 4); u32x4 wv;
;                 wv.x = pk2(bflo(qv[ks].x) * rq * g0.x, bfhi(qv[ks].x) * rq * g0.y); wv.y = pk2(bflo(qv[ks].y) * rq * g0.z, bfhi(qv[ks].y) * rq * g0.w);
;                 wv.z = pk2(bflo(qv[ks].z) * rq * g1.x, bfhi(qv[ks].z) * rq * g1.y); wv.w = pk2(bflo(qv[ks].w) * rq * g1.z, bfhi(qv[ks].w) * rq * g1.w);
;                 qf[ks] = __builtin_bit_cast(bf16x8, wv); }
.LBB0_195:
	s_cmp_eq_u32 s100, 0
	s_cbranch_scc1 .Lp1_nn5
	v_pk_mul_f32 v[156:157], v[44:45], v[44:45]
	v_pk_mul_f32 v[158:159], v[46:47], v[46:47]
	v_pk_fma_f32 v[156:157], v[40:41], v[40:41], v[156:157]
	v_pk_fma_f32 v[158:159], v[42:43], v[42:43], v[158:159]
	v_pk_fma_f32 v[156:157], v[36:37], v[36:37], v[156:157]
	v_pk_fma_f32 v[158:159], v[38:39], v[38:39], v[158:159]
	v_pk_fma_f32 v[156:157], v[32:33], v[32:33], v[156:157]
	v_pk_fma_f32 v[158:159], v[34:35], v[34:35], v[158:159]
	v_pk_add_f32 v[156:157], v[156:157], v[158:159]
	v_add_f32_e32 v156, v156, v157
	v_mov_b32_e32 v157, v156
	s_nop 1
	v_permlane16_swap_b32_e32 v156, v157
	v_add_f32_e32 v156, v156, v157
	v_mov_b32_e32 v157, v156
	s_nop 1
	v_permlane32_swap_b32_e32 v156, v157
	v_add_f32_e32 v156, v156, v157
	v_mul_f32_e32 v156, 0x3c800000, v156
	v_add_f32_e32 v156, 0x358637bd, v156
	v_rsq_f32_e32 v156, v156
	s_nop 0
	v_mul_f32_e32 v156, s101, v156
	v_pk_mul_f32 v[44:45], v[44:45], v[156:157] op_sel_hi:[1,0]
	v_pk_mul_f32 v[46:47], v[46:47], v[156:157] op_sel_hi:[1,0]
	v_pk_mul_f32 v[40:41], v[40:41], v[156:157] op_sel_hi:[1,0]
	v_pk_mul_f32 v[42:43], v[42:43], v[156:157] op_sel_hi:[1,0]
	v_pk_mul_f32 v[36:37], v[36:37], v[156:157] op_sel_hi:[1,0]
	v_pk_mul_f32 v[38:39], v[38:39], v[156:157] op_sel_hi:[1,0]
	v_pk_mul_f32 v[32:33], v[32:33], v[156:157] op_sel_hi:[1,0]
	v_pk_mul_f32 v[34:35], v[34:35], v[156:157] op_sel_hi:[1,0]
	v_pk_mul_f32 v[44:45], v[44:45], v[234:235]
	v_pk_mul_f32 v[46:47], v[46:47], v[236:237]
	v_pk_mul_f32 v[40:41], v[40:41], v[238:239]
	v_pk_mul_f32 v[42:43], v[42:43], v[240:241]
	v_pk_mul_f32 v[36:37], v[36:37], v[242:243]
	v_pk_mul_f32 v[38:39], v[38:39], v[244:245]
	v_pk_mul_f32 v[32:33], v[32:33], v[246:247]
	v_pk_mul_f32 v[34:35], v[34:35], v[248:249]

; __device__ __forceinline__ unsigned pk2(float lo, float hi) { f32x2_t v = {lo, hi}; bf16x2_t b = __builtin_convertvector(v, bf16x2_t); return __builtin_bit_cast(unsigned, b); }
; __device__ __forceinline__ float silu_f(float v) { return v * __builtin_amdgcn_rcpf(1.f + __builtin_amdgcn_exp2f(-v * LOG2E)); }
;     __device__ __forceinline__ void operator()(const pg8::f32x4 (&acc)[2][2][4][2], const pg8::Unit& u, int wr, int wc, int fr, int fq) const {
;     ...
;             for (int m = 0; m < 4; ++m) {
;                 pg8::f32x4 a0 = acc[ai][0][m][0], a1 = acc[ai][0][m][1], b0 = acc[ai][1][m][0], b1 = acc[ai][1][m][1];
;                 if (act) {
; #pragma unroll
;                     for (int e = 0; e < 4; ++e) { a0[e] = silu_f(a0[e]); a1[e] = silu_f(a1[e]); b0[e] = silu_f(b0[e]); b1[e] = silu_f(b1[e]); } }
;                 u32x4 A, B; A.x = pk2(a0[0], a0[1]); A.y = pk2(a0[2], a0[3]); A.z = pk2(a1[0], a1[1]); A.w = pk2(a1[2], a1[3]);
;                 B.x = pk2(b0[0], b0[1]); B.y = pk2(b0[2], b0[3]); B.z = pk2(b1[0], b1[1]); B.w = pk2(b1[2], b1[3]);
; template <bool FUSED> __device__ __forceinline__ void attn_phase(const Args& a, LAS unsigned char* lds, int tid, int lane, int wave) {
;     ...
;             float ss = 0.f;
; #pragma unroll
;             for (int ks = 0; ks < 4; ++ks)
; #pragma unroll
;                 for (int e = 0; e < 4; ++e) { const float lo = bflo(qv[ks][e]), hi = bfhi(qv[ks][e]); ss += lo * lo + hi * hi; }
;             ss += __shfl_xor(ss, 32);
;             const float rq = 0.125f * LOG2E * __builtin_amdgcn_rsqf(ss * (1.f / 64.f) + 1e-6f);
; #pragma unroll
;             for (int ks = 0; ks < 4; ++ks) { const f32x4 g0 = *(const f32x4*)(a.qw + hd * 64 + 16 * ks + 8 * h), g1 = *(const f32x4*)(a.qw + hd * 64 + 16 * ks + 8 * h + 4); u32x4 wv;
;                 wv.x = pk2(bflo(qv[ks].x) * rq * g0.x, bfhi(qv[ks].x) * rq * g0.y); wv.y = pk2(bflo(qv[ks].y) * rq * g0.z, bfhi(qv[ks].y) * rq * g0.w);
;                 wv.z = pk2(bflo(qv[ks].z) * rq * g1.x, bfhi(qv[ks].z) * rq * g1.y); wv.w = pk2(bflo(qv[ks].w) * rq * g1.z, bfhi(qv[ks].w) * rq * g1.w);
;                 qf[ks] = __builtin_bit_cast(bf16x8, wv); }
.LBB0_199:
	s_cmp_eq_u32 s100, 0
	s_cbranch_scc1 .Lp1_nn6
	v_pk_mul_f32 v[156:157], v[28:29], v[28:29]
	v_pk_mul_f32 v[158:159], v[30:31], v[30:31]
	v_pk_fma_f32 v[156:157], v[24:25], v[24:25], v[156:157]
	v_pk_fma_f32 v[158:159], v[26:27], v[26:27], v[158:159]
	v_pk_fma_f32 v[156:157], v[20:21], v[20:21], v[156:157]
	v_pk_fma_f32 v[158:159], v[22:23], v[22:23], v[158:159]
	v_pk_fma_f32 v[156:157], v[16:17], v[16:17], v[156:157]
	v_pk_fma_f32 v[158:159], v[18:19], v[18:19], v[158:159]
	v_pk_add_f32 v[156:157], v[156:157], v[158:159]
	v_add_f32_e32 v156, v156, v157
	v_mov_b32_e32 v157, v156
	s_nop 1
	v_permlane16_swap_b32_e32 v156, v157
	v_add_f32_e32 v156, v156, v157
	v_mov_b32_e32 v157, v156
	s_nop 1
	v_permlane32_swap_b32_e32 v156, v157
	v_add_f32_e32 v156, v156, v157
	v_mul_f32_e32 v156, 0x3c800000, v156
	v_add_f32_e32 v156, 0x358637bd, v156
	v_rsq_f32_e32 v156, v156
	s_nop 0
	v_mul_f32_e32 v156, s101, v156
	v_pk_mul_f32 v[28:29], v[28:29], v[156:157] op_sel_hi:[1,0]
	v_pk_mul_f32 v[30:31], v[30:31], v[156:157] op_sel_hi:[1,0]
	v_pk_mul_f32 v[24:25], v[24:25], v[156:157] op_sel_hi:[1,0]
	v_pk_mul_f32 v[26:27], v[26:27], v[156:157] op_sel_hi:[1,0]
	v_pk_mul_f32 v[20:21], v[20:21], v[156:157] op_sel_hi:[1,0]
	v_pk_mul_f32 v[22:23], v[22:23], v[156:157] op_sel_hi:[1,0]
	v_pk_mul_f32 v[16:17], v[16:17], v[156:157] op_sel_hi:[1,0]
	v_pk_mul_f32 v[18:19], v[18:19], v[156:157] op_sel_hi:[1,0]
	v_pk_mul_f32 v[28:29], v[28:29], v[234:235]
	v_pk_mul_f32 v[30:31], v[30:31], v[236:237]
	v_pk_mul_f32 v[24:25], v[24:25], v[238:239]
	v_pk_mul_f32 v[26:27], v[26:27], v[240:241]
	v_pk_mul_f32 v[20:21], v[20:21], v[242:243]
	v_pk_mul_f32 v[22:23], v[22:23], v[244:245]
	v_pk_mul_f32 v[16:17], v[16:17], v[246:247]
	v_pk_mul_f32 v[18:19], v[18:19], v[248:249]

; __device__ __forceinline__ unsigned pk2(float lo, float hi) { f32x2_t v = {lo, hi}; bf16x2_t b = __builtin_convertvector(v, bf16x2_t); return __builtin_bit_cast(unsigned, b); }
; __device__ __forceinline__ float silu_f(float v) { return v * __builtin_amdgcn_rcpf(1.f + __builtin_amdgcn_exp2f(-v * LOG2E)); }
;     __device__ __forceinline__ void operator()(const pg8::f32x4 (&acc)[2][2][4][2], const pg8::Unit& u, int wr, int wc, int fr, int fq) const {
;     ...
;             for (int m = 0; m < 4; ++m) {
;                 pg8::f32x4 a0 = acc[ai][0][m][0], a1 = acc[ai][0][m][1], b0 = acc[ai][1][m][0], b1 = acc[ai][1][m][1];
;                 if (act) {
; #pragma unroll
;                     for (int e = 0; e < 4; ++e) { a0[e] = silu_f(a0[e]); a1[e] = silu_f(a1[e]); b0[e] = silu_f(b0[e]); b1[e] = silu_f(b1[e]); } }
;                 u32x4 A, B; A.x = pk2(a0[0], a0[1]); A.y = pk2(a0[2], a0[3]); A.z = pk2(a1[0], a1[1]); A.w = pk2(a1[2], a1[3]);
;                 B.x = pk2(b0[0], b0[1]); B.y = pk2(b0[2], b0[3]); B.z = pk2(b1[0], b1[1]); B.w = pk2(b1[2], b1[3]);
; template <bool FUSED> __device__ __forceinline__ void attn_phase(const Args& a, LAS unsigned char* lds, int tid, int lane, int wave) {
;     ...
;             float ss = 0.f;
; #pragma unroll
;             for (int ks = 0; ks < 4; ++ks)
; #pragma unroll
;                 for (int e = 0; e < 4; ++e) { const float lo = bflo(qv[ks][e]), hi = bfhi(qv[ks][e]); ss += lo * lo + hi * hi; }
;             ss += __shfl_xor(ss, 32);
;             const float rq = 0.125f * LOG2E * __builtin_amdgcn_rsqf(ss * (1.f / 64.f) + 1e-6f);
; #pragma unroll
;             for (int ks = 0; ks < 4; ++ks) { const f32x4 g0 = *(const f32x4*)(a.qw + hd * 64 + 16 * ks + 8 * h), g1 = *(const f32x4*)(a.qw + hd * 64 + 16 * ks + 8 * h + 4); u32x4 wv;
;                 wv.x = pk2(bflo(qv[ks].x) * rq * g0.x, bfhi(qv[ks].x) * rq * g0.y); wv.y = pk2(bflo(qv[ks].y) * rq * g0.z, bfhi(qv[ks].y) * rq * g0.w);
;                 wv.z = pk2(bflo(qv[ks].z) * rq * g1.x, bfhi(qv[ks].z) * rq * g1.y); wv.w = pk2(bflo(qv[ks].w) * rq * g1.z, bfhi(qv[ks].w) * rq * g1.w);
;                 qf[ks] = __builtin_bit_cast(bf16x8, wv); }
.LBB0_203:
	s_cmp_eq_u32 s100, 0
	s_cbranch_scc1 .Lp1_nn7
	v_pk_mul_f32 v[156:157], v[12:13], v[12:13]
	v_pk_mul_f32 v[158:159], v[14:15], v[14:15]
	v_pk_fma_f32 v[156:157], v[8:9], v[8:9], v[156:157]
	v_pk_fma_f32 v[158:159], v[10:11], v[10:11], v[158:159]
	v_pk_fma_f32 v[156:157], v[4:5], v[4:5], v[156:157]
	v_pk_fma_f32 v[158:159], v[6:7], v[6:7], v[158:159]
	v_pk_fma_f32 v[156:157], v[0:1], v[0:1], v[156:157]
	v_pk_fma_f32 v[158:159], v[2:3], v[2:3], v[158:159]
	v_pk_add_f32 v[156:157], v[156:157], v[158:159]
	v_add_f32_e32 v156, v156, v157
	v_mov_b32_e32 v157, v156
	s_nop 1
	v_permlane16_swap_b32_e32 v156, v157
	v_add_f32_e32 v156, v156, v157
	v_mov_b32_e32 v157, v156
	s_nop 1
	v_permlane32_swap_b32_e32 v156, v157
	v_add_f32_e32 v156, v156, v157
	v_mul_f32_e32 v156, 0x3c800000, v156
	v_add_f32_e32 v156, 0x358637bd, v156
	v_rsq_f32_e32 v156, v156
	s_nop 0
	v_mul_f32_e32 v156, s101, v156
	v_pk_mul_f32 v[12:13], v[12:13], v[156:157] op_sel_hi:[1,0]
	v_pk_mul_f32 v[14:15], v[14:15], v[156:157] op_sel_hi:[1,0]
	v_pk_mul_f32 v[8:9], v[8:9], v[156:157] op_sel_hi:[1,0]
	v_pk_mul_f32 v[10:11], v[10:11], v[156:157] op_sel_hi:[1,0]
	v_pk_mul_f32 v[4:5], v[4:5], v[156:157] op_sel_hi:[1,0]
	v_pk_mul_f32 v[6:7], v[6:7], v[156:157] op_sel_hi:[1,0]
	v_pk_mul_f32 v[0:1], v[0:1], v[156:157] op_sel_hi:[1,0]
	v_pk_mul_f32 v[2:3], v[2:3], v[156:157] op_sel_hi:[1,0]
	v_pk_mul_f32 v[12:13], v[12:13], v[234:235]
	v_pk_mul_f32 v[14:15], v[14:15], v[236:237]
	v_pk_mul_f32 v[8:9], v[8:9], v[238:239]
	v_pk_mul_f32 v[10:11], v[10:11], v[240:241]
	v_pk_mul_f32 v[4:5], v[4:5], v[242:243]
	v_pk_mul_f32 v[6:7], v[6:7], v[244:245]
	v_pk_mul_f32 v[0:1], v[0:1], v[246:247]
	v_pk_mul_f32 v[2:3], v[2:3], v[248:249]

; template <bool FUSED> __device__ __forceinline__ void attn_phase(const Args& a, LAS unsigned char* lds, int tid, int lane, int wave) {
;     ...
;         {
;             const int ch = tid & 7;
;             const f32x4 g0 = *(const f32x4*)(a.kw + hd * 64 + ch * 8), g1 = *(const f32x4*)(a.kw + hd * 64 + ch * 8 + 4);
; #pragma unroll
;             for (int i = 0; i < 6; ++i) { const int row = (tid + 512 * i) >> 3;
;                 const float e0 = bflo(kv[i].x), e1 = bfhi(kv[i].x), e2 = bflo(kv[i].y), e3 = bfhi(kv[i].y), e4 = bflo(kv[i].z), e5 = bfhi(kv[i].z), e6 = bflo(kv[i].w), e7 = bfhi(kv[i].w);
;                 float ss = (e0 * e0 + e1 * e1) + (e2 * e2 + e3 * e3) + (e4 * e4 + e5 * e5) + (e6 * e6 + e7 * e7);
;                 ss += dpp_movf<0xB1>(ss); ss += dpp_movf<0x4E>(ss); ss += dpp_movf<0x141>(ss);
;                 const float rk = __builtin_amdgcn_rsqf(ss * (1.f / 64.f) + 1e-6f);
;                 u32x4 wv; wv.x = pk2(e0 * rk * g0.x, e1 * rk * g0.y); wv.y = pk2(e2 * rk * g0.z, e3 * rk * g0.w); wv.z = pk2(e4 * rk * g1.x, e5 * rk * g1.y); wv.w = pk2(e6 * rk * g1.z, e7 * rk * g1.w);
;                 *(LAS u32x4*)(lds + row * KP + ch * 16) = wv;
;                 *(LAS u32x4*)(lds + LDS_VOFF + row * VP + ch * 16) = vv[i];
;                 if (i & 1) __builtin_amdgcn_sched_barrier(0); }
;         }
;         bf16x8 qf[4];
;         {
;             float ss = 0.f;
; #pragma unroll
;             for (int ks = 0; ks < 4; ++ks)
; #pragma unroll
;                 for (int e = 0; e < 4; ++e) { const float lo = bflo(qv[ks][e]), hi = bfhi(qv[ks][e]); ss += lo * lo + hi * hi; }
;             ss += __shfl_xor(ss, 32);
;             const float rq = 0.125f * LOG2E * __builtin_amdgcn_rsqf(ss * (1.f / 64.f) + 1e-6f);
; #pragma unroll
;             for (int ks = 0; ks < 4; ++ks) { const f32x4 g0 = *(const f32x4*)(a.qw + hd * 64 + 16 * ks + 8 * h), g1 = *(const f32x4*)(a.qw + hd * 64 + 16 * ks + 8 * h + 4); u32x4 wv;
;                 wv.x = pk2(bflo(qv[ks].x) * rq * g0.x, bfhi(qv[ks].x) * rq * g0.y); wv.y = pk2(bflo(qv[ks].y) * rq * g0.z, bfhi(qv[ks].y) * rq * g0.w);
;                 wv.z = pk2(bflo(qv[ks].z) * rq * g1.x, bfhi(qv[ks].z) * rq * g1.y); wv.w = pk2(bflo(qv[ks].w) * rq * g1.z, bfhi(qv[ks].w) * rq * g1.w);
;                 qf[ks] = __builtin_bit_cast(bf16x8, wv); }
;         }
;         const float mb = ((const float*)(a.ws + WS_RS))[hd];
.LBB0_280:
	s_ashr_i32 s6, s67, 5
	s_lshr_b32 s7, s6, 28
	s_add_i32 s7, s6, s7
	s_and_b32 s7, s7, -16
	s_sub_i32 s66, s6, s7
	s_add_i32 s68, s66, 8
	s_ashr_i32 s69, s68, 31
	s_lshl_b64 s[6:7], s[68:69], 2
	s_add_u32 s6, s87, s6
	s_addc_u32 s7, s88, s7
	global_load_dword v222, v147, s[6:7]
	s_waitcnt vmcnt(15)
	ds_write_b128 v177, v[64:67]
	ds_write_b128 v188, v[68:71] offset:55296
	s_waitcnt vmcnt(13)
	ds_write_b128 v189, v[72:75]
	ds_write_b128 v190, v[76:79] offset:55296
	s_waitcnt vmcnt(11)
	ds_write_b128 v191, v[80:83]
	ds_write_b128 v192, v[84:87] offset:55296
	s_waitcnt vmcnt(9)
	ds_write_b128 v193, v[96:99]
	ds_write_b128 v194, v[104:107] offset:55296
	s_waitcnt vmcnt(7)
	ds_write_b128 v195, v[112:115]
	ds_write_b128 v196, v[116:119] offset:55296
	s_waitcnt vmcnt(5)
	ds_write_b128 v197, v[120:123]
	ds_write_b128 v198, v[124:127] offset:55296
	s_add_i32 s69, s67, s54
	s_cmpk_lt_i32 s69, 0x1000
	s_cselect_b64 s[72:73], -1, 0
	s_cmpk_gt_i32 s69, 0xfff
	s_cselect_b64 s[70:71], -1, 0
	s_and_b64 vcc, exec, s[70:71]
	s_waitcnt vmcnt(1)
	v_mov_b32_e32 v136, v88
	v_mov_b32_e32 v137, v89
	v_mov_b32_e32 v138, v90
	v_mov_b32_e32 v139, v91
	v_mov_b32_e32 v132, v92
	v_mov_b32_e32 v133, v93
	v_mov_b32_e32 v134, v94
	v_mov_b32_e32 v135, v95
	v_mov_b32_e32 v128, v100
	v_mov_b32_e32 v129, v101
	v_mov_b32_e32 v130, v102
	v_mov_b32_e32 v131, v103
	v_mov_b32_e32 v140, v108
	v_mov_b32_e32 v141, v109
	v_mov_b32_e32 v142, v110
	v_mov_b32_e32 v143, v111
	s_waitcnt lgkmcnt(0)
	s_barrier
	s_cbranch_vccnz .LBB0_282
	s_ashr_i32 s7, s69, 5
	s_lshr_b32 s8, s7, 28
	s_add_i32 s8, s7, s8
	s_and_b32 s8, s8, -16
	s_sub_i32 s7, s7, s8
	s_add_i32 s7, s7, 8
	s_ashr_i32 s9, s7, 2
	s_and_b32 s9, s9, -2
	s_lshr_b32 s10, 32, s9
	s_and_b32 s6, s69, 31
	s_lshr_b32 s11, 0x2000, s9
	s_sub_i32 s9, 5, s9
	s_add_i32 s10, s10, -1
	s_lshr_b32 s9, s6, s9
	s_and_b32 s6, s10, s6
	s_lshl_b32 s10, s6, 8
	v_add_u32_e32 v42, s10, v155
	s_add_i32 s12, s11, -1
	v_min_i32_e32 v45, s12, v42
	v_cmp_lt_i32_e32 vcc, -1, v42
	s_mul_i32 s9, s9, s11
	s_ashr_i32 s8, s69, 31
	v_cndmask_b32_e32 v42, 0, v45, vcc
	v_add_u32_e32 v64, s9, v42
	v_add_u32_e32 v42, s10, v170
	v_min_i32_e32 v45, s12, v42
	v_cmp_lt_i32_e32 vcc, -1, v42
	s_lshr_b32 s8, s8, 23
	s_add_i32 s8, s69, s8
	v_cndmask_b32_e32 v42, 0, v45, vcc
	v_add_u32_e32 v72, s9, v42
	v_add_u32_e32 v42, s10, v171
	v_min_i32_e32 v45, s12, v42
	v_cmp_lt_i32_e32 vcc, -1, v42
	s_ashr_i32 s8, s8, 9
	s_mul_i32 s8, s8, 24
	v_cndmask_b32_e32 v42, 0, v45, vcc
	v_add_u32_e32 v80, s9, v42
	v_add_u32_e32 v42, s10, v172
	v_min_i32_e32 v45, s12, v42
	v_cmp_lt_i32_e32 vcc, -1, v42
	s_add_i32 s6, s7, s8
	s_ashr_i32 s7, s6, 31
	v_cndmask_b32_e32 v42, 0, v45, vcc
	v_add_u32_e32 v96, s9, v42
	v_add_u32_e32 v42, s10, v173
	v_min_i32_e32 v45, s12, v42
	v_cmp_lt_i32_e32 vcc, -1, v42
	v_ashrrev_i32_e32 v65, 31, v64
	v_ashrrev_i32_e32 v73, 31, v72
	v_cndmask_b32_e32 v42, 0, v45, vcc
	v_add_u32_e32 v112, s9, v42
	v_add_u32_e32 v42, s10, v174
	v_min_i32_e32 v45, s12, v42
	v_cmp_lt_i32_e32 vcc, -1, v42
	v_ashrrev_i32_e32 v81, 31, v80
	v_ashrrev_i32_e32 v97, 31, v96
	v_cndmask_b32_e32 v42, 0, v45, vcc
	v_add_u32_e32 v120, s9, v42
	v_ashrrev_i32_e32 v113, 31, v112
	v_ashrrev_i32_e32 v121, 31, v120
	s_lshl_b64 s[6:7], s[6:7], 19
	v_lshlrev_b64 v[64:65], 6, v[64:65]
	v_lshlrev_b64 v[72:73], 6, v[72:73]
	v_lshlrev_b64 v[80:81], 6, v[80:81]
	v_lshlrev_b64 v[96:97], 6, v[96:97]
	v_lshlrev_b64 v[112:113], 6, v[112:113]
	v_lshlrev_b64 v[120:121], 6, v[120:121]
	v_lshl_add_u64 v[64:65], v[64:65], 0, s[6:7]
	v_lshl_add_u64 v[72:73], v[72:73], 0, s[6:7]
	v_lshl_add_u64 v[80:81], v[80:81], 0, s[6:7]
	v_lshl_add_u64 v[96:97], v[96:97], 0, s[6:7]
	v_lshl_add_u64 v[112:113], v[112:113], 0, s[6:7]
	v_lshl_add_u64 v[120:121], v[120:121], 0, s[6:7]
	v_or_b32_e32 v64, v64, v144
	v_or_b32_e32 v72, v72, v144
	v_or_b32_e32 v80, v80, v144
	v_or_b32_e32 v96, v96, v144
	v_or_b32_e32 v112, v112, v144
	v_or_b32_e32 v120, v120, v144
	v_lshlrev_b64 v[64:65], 1, v[64:65]
	v_lshlrev_b64 v[72:73], 1, v[72:73]
	v_lshlrev_b64 v[80:81], 1, v[80:81]
	v_lshlrev_b64 v[96:97], 1, v[96:97]
	v_lshlrev_b64 v[112:113], 1, v[112:113]
	v_lshlrev_b64 v[120:121], 1, v[120:121]
	v_lshl_add_u64 v[66:67], s[58:59], 0, v[64:65]
	v_lshl_add_u64 v[68:69], s[60:61], 0, v[64:65]
	v_lshl_add_u64 v[74:75], s[58:59], 0, v[72:73]
	v_lshl_add_u64 v[76:77], s[60:61], 0, v[72:73]
	v_lshl_add_u64 v[82:83], s[58:59], 0, v[80:81]
	v_lshl_add_u64 v[84:85], s[60:61], 0, v[80:81]
	v_lshl_add_u64 v[98:99], s[58:59], 0, v[96:97]
	v_lshl_add_u64 v[104:105], s[60:61], 0, v[96:97]
	v_lshl_add_u64 v[114:115], s[58:59], 0, v[112:113]
	v_lshl_add_u64 v[116:117], s[60:61], 0, v[112:113]
	v_lshl_add_u64 v[122:123], s[58:59], 0, v[120:121]
	v_lshl_add_u64 v[124:125], s[60:61], 0, v[120:121]
	global_load_dwordx4 v[64:67], v[66:67], off
	s_nop 0
	global_load_dwordx4 v[68:71], v[68:69], off
	s_nop 0
	global_load_dwordx4 v[72:75], v[74:75], off
	s_nop 0
	global_load_dwordx4 v[76:79], v[76:77], off
	s_nop 0
	global_load_dwordx4 v[80:83], v[82:83], off
	s_nop 0
	global_load_dwordx4 v[84:87], v[84:85], off
	s_nop 0
	global_load_dwordx4 v[96:99], v[98:99], off
	s_nop 0
	global_load_dwordx4 v[104:107], v[104:105], off
	s_nop 0
	global_load_dwordx4 v[112:115], v[114:115], off
	s_nop 0
	global_load_dwordx4 v[116:119], v[116:117], off
	s_nop 0
	global_load_dwordx4 v[120:123], v[122:123], off
	s_nop 0
	global_load_dwordx4 v[124:127], v[124:125], off
	s_and_b32 s7, s66, 7
	s_add_i32 s7, s7, 1
	s_ashr_i32 s6, s68, 2
	s_and_b32 s75, s6, -2
	s_lshr_b32 s6, 32, s75
	v_mov_b32_e32 v48, v175
	ds_read_b128 v[42:45], v199 offset:32
	ds_read_b128 v[38:41], v199
	v_cvt_f32_ubyte0_e32 v32, s7
	s_waitcnt vmcnt(12)
	s_branch .Lattn1_join
; #define LAS __attribute__((address_space(3)))
; __device__ __forceinline__ float attn_tile_exp(f32x16& st, int j, float tlf, float bsl, float rlo, float rhi) {
;     float sum = 0.f;
; #pragma unroll
;     for (int i = 0; i < 16; ++i) { const float tmp = (float)(32 * j - 64 + (i & 3) + 8 * (i >> 2)) + tlf;
;         float arg = __builtin_fmaf(-bsl, __builtin_fabsf(tmp), st[i]);
;         arg = (tmp >= rlo && tmp <= rhi) ? arg : -1.0e30f;
;         const float pe = __builtin_amdgcn_exp2f(arg); st[i] = pe; sum += pe; }
;     return sum;
; template <bool FUSED> __device__ __forceinline__ void attn_phase(const Args& a, LAS unsigned char* lds, int tid, int lane, int wave) {
;     ...
;         const float mb = ((const float*)(a.ws + WS_RS))[hd];
;         __syncthreads();
;         const int un = u + gridDim.x;
;         if (un < NU) { const AUnit wn = attn_decode(un, HD0, NH); attn_issue(wn, Qb, Kb, Vb, tid, wave, lane, kv, vv); }
;         const float bsl = __builtin_amdgcn_exp2f(-(float)(slot + 1)) * (float)w.dil * LOG2E;
;         int tl = 4 * h - l31; asm volatile("" : "+v"(tl));
;         const float tlf = (float)tl;
;         const int lo_i = -iq > -64 ? -iq : -64, hi_i = (L - 1 - iq) < 64 ? (L - 1 - iq) : 64;
;         const float rlo = (float)lo_i, rhi = (float)hi_i;
;         const int wq0 = i0 + 32 * wave;
;         const bool edge = (wq0 < 64) || (wq0 + 32 > L - 64);
;         float sum = 0.f;
;         f32x16 o[2]; o[0] = f32x16{}; o[1] = f32x16{};
; #pragma unroll
;         for (int j = 0; j < 5; ++j) {
;             f32x16 st;
; #pragma unroll
;             for (int i = 0; i < 16; ++i) st[i] = -mb;
;             LAS const unsigned char* kp = lds + (32 * wave + 32 * j + l31) * KP + 16 * h;
; #pragma unroll
;             for (int ks = 0; ks < 4; ++ks) { const bf16x8 kf = *(LAS const bf16x8*)(kp + 32 * ks); st = __builtin_amdgcn_mfma_f32_32x32x16_bf16(kf, qf[ks], st, 0, 0, 0); }
;             sum += attn_tile_exp(st, j, tlf, bsl, rlo, rhi);
.LBB0_282:
	s_and_b32 s7, s66, 7
	s_add_i32 s7, s7, 1
	s_ashr_i32 s6, s68, 2
	s_and_b32 s75, s6, -2
	s_lshr_b32 s6, 32, s75
	v_mov_b32_e32 v48, v175
	ds_read_b128 v[42:45], v199 offset:32
	ds_read_b128 v[38:41], v199
	v_cvt_f32_ubyte0_e32 v32, s7
	s_waitcnt vmcnt(0)
.Lattn1_join:
	v_xor_b32_e32 v0, 0x80000000, v222
	v_mov_b32_e32 v1, v0
	v_mov_b32_e32 v2, v0
	v_mov_b32_e32 v3, v0
	v_mov_b32_e32 v4, v0
	v_mov_b32_e32 v5, v0
	v_mov_b32_e32 v6, v0
	v_mov_b32_e32 v7, v0
	v_mov_b32_e32 v8, v0
	v_mov_b32_e32 v9, v0
	v_mov_b32_e32 v10, v0
	v_mov_b32_e32 v11, v0
	v_mov_b32_e32 v12, v0
	v_mov_b32_e32 v13, v0
	v_mov_b32_e32 v14, v0
	v_mov_b32_e32 v15, v0
	v_exp_f32_e64 v46, -v32
	s_waitcnt lgkmcnt(0)
	v_mfma_f32_32x32x16_bf16 v[16:31], v[38:41], v[136:139], v[0:15]
	ds_read_b128 v[38:41], v199 offset:64
	s_and_b32 s77, s67, 31
	ds_read_b128 v[32:35], v199 offset:96
	s_add_i32 s6, s6, -1
	s_and_b32 s6, s6, s77
	v_mfma_f32_32x32x16_bf16 v[16:31], v[42:45], v[132:135], v[16:31]
	s_lshr_b32 s76, 0x2000, s75
	v_lshl_add_u32 v168, s6, 8, v145
	s_lshl_b32 s6, 1, s75
	v_sub_u32_e32 v37, 0, v168
	v_cvt_f32_u32_e32 v42, s6
	v_cvt_f32_i32_e32 v225, v48
	v_max_i32_e32 v37, 0xffffffc0, v37
	s_waitcnt lgkmcnt(1)
	v_mfma_f32_32x32x16_bf16 v[16:31], v[38:41], v[128:131], v[16:31]
	v_xad_u32 v38, v168, -1, s76
	v_min_i32_e32 v38, 64, v38
	v_cvt_f32_i32_e32 v169, v37
	v_cvt_f32_i32_e32 v223, v38
	v_mul_f32_e32 v36, v46, v42
	v_mul_f32_e32 v224, 0xbfb8aa3b, v36
	s_waitcnt lgkmcnt(0)
	v_mfma_f32_32x32x16_bf16 v[16:31], v[32:35], v[140:143], v[16:31]
	v_add_f32_e32 v32, 0xc2800000, v225
	v_cmp_nge_f32_e32 vcc, v32, v169
	v_cmp_nle_f32_e64 s[6:7], v32, v223
	s_or_b64 vcc, vcc, s[6:7]
	v_add_f32_e32 v33, 0xc27c0000, v225
	v_cmp_nle_f32_e64 s[6:7], v33, v223
	s_nop 5
	v_fma_f32 v16, v224, |v32|, v16
	v_cndmask_b32_e32 v16, v16, v221, vcc
	v_cmp_nge_f32_e32 vcc, v33, v169
	v_fma_f32 v17, v224, |v33|, v17
	s_or_b64 vcc, vcc, s[6:7]
	v_cndmask_b32_e32 v17, v17, v221, vcc
	v_exp_f32_e32 v33, v17
	v_add_f32_e32 v17, 0xc2780000, v225
	v_cmp_nge_f32_e32 vcc, v17, v169
	v_cmp_nle_f32_e64 s[6:7], v17, v223
	v_fma_f32 v18, v224, |v17|, v18
	s_or_b64 vcc, vcc, s[6:7]
	v_cndmask_b32_e32 v17, v18, v221, vcc
	v_exp_f32_e32 v34, v17
	v_add_f32_e32 v17, 0xc2740000, v225
	v_cmp_nge_f32_e32 vcc, v17, v169
	v_cmp_nle_f32_e64 s[6:7], v17, v223
	v_fma_f32 v18, v224, |v17|, v19
	s_or_b64 vcc, vcc, s[6:7]
	v_cndmask_b32_e32 v17, v18, v221, vcc
	v_exp_f32_e32 v35, v17
	v_add_f32_e32 v17, 0xc2600000, v225
	v_cmp_nge_f32_e32 vcc, v17, v169
	v_cmp_nle_f32_e64 s[6:7], v17, v223
	v_fma_f32 v18, v224, |v17|, v20
	s_or_b64 vcc, vcc, s[6:7]
	v_cndmask_b32_e32 v17, v18, v221, vcc
	v_exp_f32_e32 v36, v17
	v_add_f32_e32 v17, 0xc25c0000, v225
	v_cmp_nge_f32_e32 vcc, v17, v169
	v_cmp_nle_f32_e64 s[6:7], v17, v223
	v_fma_f32 v18, v224, |v17|, v21
	s_or_b64 vcc, vcc, s[6:7]
	v_cndmask_b32_e32 v17, v18, v221, vcc
	v_exp_f32_e32 v37, v17
	v_add_f32_e32 v17, 0xc2580000, v225
	v_cmp_nge_f32_e32 vcc, v17, v169
	v_cmp_nle_f32_e64 s[6:7], v17, v223
	v_fma_f32 v18, v224, |v17|, v22
	s_or_b64 vcc, vcc, s[6:7]
	v_cndmask_b32_e32 v17, v18, v221, vcc
	v_exp_f32_e32 v32, v16
	v_exp_f32_e32 v38, v17
	v_add_f32_e32 v17, 0xc2540000, v225
	v_cmp_nge_f32_e32 vcc, v17, v169
	v_cmp_nle_f32_e64 s[6:7], v17, v223
	v_fma_f32 v18, v224, |v17|, v23
	s_or_b64 vcc, vcc, s[6:7]
	v_cndmask_b32_e32 v17, v18, v221, vcc
	v_add_f32_e32 v16, 0, v32
	v_exp_f32_e32 v23, v17
	v_add_f32_e32 v17, 0xc2400000, v225
	v_add_f32_e32 v16, v33, v16
	v_cmp_nge_f32_e32 vcc, v17, v169
	v_cmp_nle_f32_e64 s[6:7], v17, v223
	v_add_f32_e32 v16, v34, v16
	v_fma_f32 v18, v224, |v17|, v24
	s_or_b64 vcc, vcc, s[6:7]
	v_add_f32_e32 v16, v35, v16
	v_cndmask_b32_e32 v17, v18, v221, vcc
	v_add_f32_e32 v16, v36, v16
	v_exp_f32_e32 v52, v17
	v_add_f32_e32 v16, v37, v16
	v_add_f32_e32 v16, v38, v16
	v_add_f32_e32 v16, v23, v16
	v_add_f32_e32 v60, v52, v16
	v_add_f32_e32 v16, 0xc23c0000, v225
	v_cmp_nge_f32_e32 vcc, v16, v169
	v_cmp_nle_f32_e64 s[6:7], v16, v223
	v_fma_f32 v17, v224, |v16|, v25
	s_or_b64 vcc, vcc, s[6:7]
	v_cndmask_b32_e32 v16, v17, v221, vcc
	v_exp_f32_e32 v61, v16
	v_add_f32_e32 v16, 0xc2380000, v225
	v_cmp_nge_f32_e32 vcc, v16, v169
	v_cmp_nle_f32_e64 s[6:7], v16, v223
	v_fma_f32 v17, v224, |v16|, v26
	s_or_b64 vcc, vcc, s[6:7]
	v_cndmask_b32_e32 v16, v17, v221, vcc
	v_exp_f32_e32 v62, v16
	v_add_f32_e32 v16, 0xc2340000, v225
	v_cmp_nge_f32_e32 vcc, v16, v169
	v_cmp_nle_f32_e64 s[6:7], v16, v223
	v_fma_f32 v17, v224, |v16|, v27
	s_or_b64 vcc, vcc, s[6:7]
	v_cndmask_b32_e32 v16, v17, v221, vcc
	v_exp_f32_e32 v63, v16
	v_add_f32_e32 v16, 0xc2200000, v225
	v_cmp_nge_f32_e32 vcc, v16, v169
	v_cmp_nle_f32_e64 s[6:7], v16, v223
	v_fma_f32 v17, v224, |v16|, v28
	s_or_b64 vcc, vcc, s[6:7]
	v_cndmask_b32_e32 v16, v17, v221, vcc
	v_exp_f32_e32 v226, v16
	v_add_f32_e32 v16, 0xc21c0000, v225
	v_cmp_nge_f32_e32 vcc, v16, v169
	v_cmp_nle_f32_e64 s[6:7], v16, v223
	v_fma_f32 v17, v224, |v16|, v29
	s_or_b64 vcc, vcc, s[6:7]
	v_cndmask_b32_e32 v16, v17, v221, vcc
	v_exp_f32_e32 v227, v16
	v_add_f32_e32 v16, 0xc2180000, v225
	v_cmp_nge_f32_e32 vcc, v16, v169
	v_cmp_nle_f32_e64 s[6:7], v16, v223
	v_fma_f32 v17, v224, |v16|, v30
	s_or_b64 vcc, vcc, s[6:7]
	v_cndmask_b32_e32 v20, v17, v221, vcc
	ds_read_b64_tr_b16 v[16:17], v200 offset:55296
	ds_read_b64_tr_b16 v[18:19], v200 offset:56832
	ds_read_b64_tr_b16 v[26:27], v200 offset:56896
	ds_read_b64_tr_b16 v[24:25], v200 offset:55360
	v_add_f32_e32 v28, 0xc2140000, v225
	v_exp_f32_e32 v228, v20
	v_cvt_pk_bf16_f32 v20, v32, v33
	v_cvt_pk_bf16_f32 v21, v34, v35
	v_cvt_pk_bf16_f32 v22, v36, v37
	v_cvt_pk_bf16_f32 v23, v38, v23
	v_cmp_nge_f32_e32 vcc, v28, v169
	v_cmp_nle_f32_e64 s[6:7], v28, v223
	s_waitcnt lgkmcnt(2)
	v_mfma_f32_32x32x16_bf16 v[32:47], v[16:19], v[20:23], 0
	v_fma_f32 v16, v224, |v28|, v31
	s_or_b64 vcc, vcc, s[6:7]
	v_cndmask_b32_e32 v53, v16, v221, vcc
	ds_read_b64_tr_b16 v[48:49], v200 offset:58368
	ds_read_b64_tr_b16 v[50:51], v200 offset:59904
	v_exp_f32_e32 v229, v53
	ds_read_b64_tr_b16 v[58:59], v200 offset:59968
	ds_read_b64_tr_b16 v[56:57], v200 offset:58432
	v_cvt_pk_bf16_f32 v52, v52, v61
	s_waitcnt lgkmcnt(4)
	v_mfma_f32_32x32x16_bf16 v[16:31], v[24:27], v[20:23], 0
	v_cvt_pk_bf16_f32 v53, v62, v63
	v_cvt_pk_bf16_f32 v54, v226, v227
	v_cvt_pk_bf16_f32 v55, v228, v229
	s_waitcnt lgkmcnt(2)
	s_nop 0
	v_mfma_f32_32x32x16_bf16 v[32:47], v[48:51], v[52:55], v[32:47]
	v_add_f32_e32 v48, v61, v60
	v_add_f32_e32 v48, v62, v48
	v_add_f32_e32 v48, v63, v48
	v_add_f32_e32 v48, v226, v48
	v_add_f32_e32 v48, v227, v48
	v_add_f32_e32 v48, v228, v48
	v_add_f32_e32 v48, v229, v48
	s_waitcnt lgkmcnt(0)
	v_mfma_f32_32x32x16_bf16 v[16:31], v[56:59], v[52:55], v[16:31]
	v_add_f32_e32 v238, 0, v48
	v_cmp_neq_f32_e32 vcc, 0xc2800000, v169
	s_mov_b64 s[6:7], vcc
	v_cmp_neq_f32_e32 vcc, 0x42800000, v223
	s_or_b64 vcc, vcc, s[6:7]
	s_cbranch_vccnz .Lattn1_slow
; #define LAS __attribute__((address_space(3)))
; __device__ __forceinline__ unsigned pk2(float lo, float hi) { f32x2_t v = {lo, hi}; bf16x2_t b = __builtin_convertvector(v, bf16x2_t); return __builtin_bit_cast(unsigned, b); }
; __device__ __forceinline__ s16x4 trrd(LAS const unsigned char* p) { return __builtin_bit_cast(s16x4, __builtin_amdgcn_ds_read_tr16_b64_v4i16((LAS v4i16_t*)p)); }
; __device__ __forceinline__ float attn_tile_exp(f32x16& st, int j, float tlf, float bsl, float rlo, float rhi) {
;     float sum = 0.f;
; #pragma unroll
;     for (int i = 0; i < 16; ++i) { const float tmp = (float)(32 * j - 64 + (i & 3) + 8 * (i >> 2)) + tlf;
;         float arg = __builtin_fmaf(-bsl, __builtin_fabsf(tmp), st[i]);
;         arg = (tmp >= rlo && tmp <= rhi) ? arg : -1.0e30f;
;         const float pe = __builtin_amdgcn_exp2f(arg); st[i] = pe; sum += pe; }
;     return sum;
; template <bool FUSED> __device__ __forceinline__ void attn_phase(const Args& a, LAS unsigned char* lds, int tid, int lane, int wave) {
;     ...
;         for (int j = 0; j < 5; ++j) {
;             f32x16 st;
; #pragma unroll
;             for (int i = 0; i < 16; ++i) st[i] = -mb;
;             LAS const unsigned char* kp = lds + (32 * wave + 32 * j + l31) * KP + 16 * h;
; #pragma unroll
;             for (int ks = 0; ks < 4; ++ks) { const bf16x8 kf = *(LAS const bf16x8*)(kp + 32 * ks); st = __builtin_amdgcn_mfma_f32_32x32x16_bf16(kf, qf[ks], st, 0, 0, 0); }
;             sum += attn_tile_exp(st, j, tlf, bsl, rlo, rhi);
; #pragma unroll
;             for (int s2 = 0; s2 < 2; ++s2) { u32x4 pw; pw.x = pk2(st[8 * s2 + 0], st[8 * s2 + 1]); pw.y = pk2(st[8 * s2 + 2], st[8 * s2 + 3]); pw.z = pk2(st[8 * s2 + 4], st[8 * s2 + 5]); pw.w = pk2(st[8 * s2 + 6], st[8 * s2 + 7]);
;                 const bf16x8 pf = __builtin_bit_cast(bf16x8, pw);
;                 LAS const unsigned char* vp = lds + LDS_VOFF + (32 * wave + 32 * j + 16 * s2 + 4 * h + q) * VP + 32 * blk + 8 * p;
; #pragma unroll
;                 for (int dt = 0; dt < 2; ++dt) { const s16x4 lo = trrd(vp + dt * 64), hi = trrd(vp + 8 * VP + dt * 64);
;                     const bf16x8 vf = __builtin_shufflevector(lo, hi, 0, 1, 2, 3, 4, 5, 6, 7);
;                     o[dt] = __builtin_amdgcn_mfma_f32_32x32x16_bf16(vf, pf, o[dt], 0, 0, 0); } }
;             __builtin_amdgcn_sched_barrier(0);
;         }
	ds_read_b128 v[226:229], v201
	ds_read_b128 v[230:233], v201 offset:32
	v_add_f32_e32 v239, 0xc2000000, v225
	v_add_f32_e32 v240, 0xc1f80000, v225
	s_waitcnt lgkmcnt(1)
	v_mfma_f32_32x32x16_bf16 v[48:63], v[226:229], v[136:139], v[0:15]
	ds_read_b128 v[226:229], v201 offset:64
	ds_read_b128 v[234:237], v201 offset:96
	v_add_f32_e32 v241, 0xc1f00000, v225
	v_add_f32_e32 v242, 0xc1e80000, v225
	s_waitcnt lgkmcnt(2)
	v_mfma_f32_32x32x16_bf16 v[48:63], v[230:233], v[132:135], v[48:63]
	v_add_f32_e32 v230, 0xc1c00000, v225
	v_add_f32_e32 v231, 0xc1b80000, v225
	s_waitcnt lgkmcnt(1)
	v_mfma_f32_32x32x16_bf16 v[48:63], v[226:229], v[128:131], v[48:63]
	s_waitcnt lgkmcnt(0)
	v_mfma_f32_32x32x16_bf16 v[48:63], v[234:237], v[140:143], v[48:63]
	s_nop 11
	v_fma_f32 v48, v224, |v239|, v48
	v_fma_f32 v49, v224, |v240|, v49
	v_fma_f32 v50, v224, |v241|, v50
	v_fma_f32 v51, v224, |v242|, v51
	v_fma_f32 v52, v224, |v230|, v52
	v_fma_f32 v53, v224, |v231|, v53
	v_exp_f32_e32 v227, v49
	v_mov_b32_e32 v49, v53
	v_exp_f32_e32 v231, v49
	v_add_f32_e32 v49, 0xc1b00000, v225
	v_exp_f32_e32 v228, v50
	v_fma_f32 v49, v224, |v49|, v54
	v_exp_f32_e32 v226, v48
	v_exp_f32_e32 v232, v49
	v_add_f32_e32 v49, 0xc1a80000, v225
	v_fma_f32 v49, v224, |v49|, v55
	v_exp_f32_e32 v229, v51
	v_exp_f32_e32 v230, v52
	v_add_f32_e32 v48, 0, v226
	v_exp_f32_e32 v55, v49
	v_add_f32_e32 v49, 0xc1800000, v225
	v_add_f32_e32 v48, v227, v48
	v_add_f32_e32 v48, v228, v48
	v_fma_f32 v49, v224, |v49|, v56
	v_add_f32_e32 v48, v229, v48
	v_add_f32_e32 v48, v230, v48
	v_exp_f32_e32 v233, v49
	v_add_f32_e32 v48, v231, v48
	v_add_f32_e32 v48, v232, v48
	v_add_f32_e32 v48, v55, v48
	v_add_f32_e32 v234, v233, v48
	v_add_f32_e32 v48, 0xc1700000, v225
	v_fma_f32 v48, v224, |v48|, v57
	v_exp_f32_e32 v235, v48
	v_add_f32_e32 v48, 0xc1600000, v225
	v_fma_f32 v48, v224, |v48|, v58
	v_exp_f32_e32 v236, v48
	v_add_f32_e32 v48, 0xc1500000, v225
	v_fma_f32 v48, v224, |v48|, v59
	v_exp_f32_e32 v237, v48
	v_add_f32_e32 v48, 0xc1000000, v225
	v_fma_f32 v48, v224, |v48|, v60
	v_exp_f32_e32 v60, v48
	v_add_f32_e32 v48, 0xc0e00000, v225
	v_fma_f32 v48, v224, |v48|, v61
	v_exp_f32_e32 v61, v48
	v_add_f32_e32 v48, 0xc0c00000, v225
	v_fma_f32 v52, v224, |v48|, v62
	ds_read_b64_tr_b16 v[48:49], v202 offset:55296
	ds_read_b64_tr_b16 v[50:51], v202 offset:56832
	ds_read_b64_tr_b16 v[58:59], v202 offset:56896
	ds_read_b64_tr_b16 v[56:57], v202 offset:55360
	v_exp_f32_e32 v62, v52
	v_add_f32_e32 v239, 0xc0a00000, v225
	v_cvt_pk_bf16_f32 v52, v226, v227
	v_cvt_pk_bf16_f32 v53, v228, v229
	v_cvt_pk_bf16_f32 v54, v230, v231
	v_cvt_pk_bf16_f32 v55, v232, v55
	s_waitcnt lgkmcnt(2)
	s_nop 0
	v_mfma_f32_32x32x16_bf16 v[32:47], v[48:51], v[52:55], v[32:47]
	v_fma_f32 v63, v224, |v239|, v63
	ds_read_b64_tr_b16 v[48:49], v202 offset:58368
	ds_read_b64_tr_b16 v[50:51], v202 offset:59904
	v_exp_f32_e32 v63, v63
	s_waitcnt lgkmcnt(2)
	v_mfma_f32_32x32x16_bf16 v[16:31], v[56:59], v[52:55], v[16:31]
	ds_read_b64_tr_b16 v[58:59], v202 offset:59968
	ds_read_b64_tr_b16 v[56:57], v202 offset:58432
	v_cvt_pk_bf16_f32 v52, v233, v235
	v_cvt_pk_bf16_f32 v53, v236, v237
	v_cvt_pk_bf16_f32 v54, v60, v61
	v_cvt_pk_bf16_f32 v55, v62, v63
	s_waitcnt lgkmcnt(2)
	s_nop 0
	v_mfma_f32_32x32x16_bf16 v[32:47], v[48:51], v[52:55], v[32:47]
	v_add_f32_e32 v48, v235, v234
	v_add_f32_e32 v48, v236, v48
	v_add_f32_e32 v48, v237, v48
	v_add_f32_e32 v48, v60, v48
	v_add_f32_e32 v48, v61, v48
	v_add_f32_e32 v48, v62, v48
	v_add_f32_e32 v48, v63, v48
	s_waitcnt lgkmcnt(0)
	v_mfma_f32_32x32x16_bf16 v[16:31], v[56:59], v[52:55], v[16:31]
	v_add_f32_e32 v238, v238, v48
	ds_read_b128 v[226:229], v203
	ds_read_b128 v[230:233], v203 offset:32
	v_add_f32_e32 v239, 1.0, v225
	s_waitcnt lgkmcnt(1)
	v_mfma_f32_32x32x16_bf16 v[48:63], v[226:229], v[136:139], v[0:15]
	ds_read_b128 v[226:229], v203 offset:64
	ds_read_b128 v[234:237], v203 offset:96
	s_waitcnt lgkmcnt(2)
	v_mfma_f32_32x32x16_bf16 v[48:63], v[230:233], v[132:135], v[48:63]
	v_add_f32_e32 v230, 2.0, v225
	v_add_f32_e32 v231, 0x40400000, v225
	v_add_f32_e32 v232, 0x41000000, v225
	s_waitcnt lgkmcnt(1)
	v_mfma_f32_32x32x16_bf16 v[48:63], v[226:229], v[128:131], v[48:63]
	v_add_f32_e32 v233, 0x41100000, v225
	s_waitcnt lgkmcnt(0)
	v_mfma_f32_32x32x16_bf16 v[48:63], v[234:237], v[140:143], v[48:63]
	s_nop 11
	v_fma_f32 v48, v224, |v225|, v48
	v_fma_f32 v49, v224, |v239|, v49
	v_fma_f32 v50, v224, |v230|, v50
	v_fma_f32 v51, v224, |v231|, v51
	v_fma_f32 v52, v224, |v232|, v52
	v_fma_f32 v53, v224, |v233|, v53
	v_exp_f32_e32 v227, v49
	v_mov_b32_e32 v49, v53
	v_exp_f32_e32 v231, v49
	v_add_f32_e32 v49, 0x41200000, v225
	v_exp_f32_e32 v228, v50
	v_fma_f32 v49, v224, |v49|, v54
	v_exp_f32_e32 v226, v48
	v_exp_f32_e32 v232, v49
	v_add_f32_e32 v49, 0x41300000, v225
	v_fma_f32 v49, v224, |v49|, v55
	v_exp_f32_e32 v229, v51
	v_exp_f32_e32 v230, v52
	v_add_f32_e32 v48, 0, v226
	v_exp_f32_e32 v55, v49
	v_add_f32_e32 v49, 0x41800000, v225
	v_add_f32_e32 v48, v227, v48
	v_add_f32_e32 v48, v228, v48
	v_fma_f32 v49, v224, |v49|, v56
	v_add_f32_e32 v48, v229, v48
	v_add_f32_e32 v48, v230, v48
	v_exp_f32_e32 v233, v49
	v_add_f32_e32 v48, v231, v48
	v_add_f32_e32 v48, v232, v48
	v_add_f32_e32 v48, v55, v48
	v_add_f32_e32 v234, v233, v48
	v_add_f32_e32 v48, 0x41880000, v225
	v_fma_f32 v48, v224, |v48|, v57
	v_exp_f32_e32 v235, v48
	v_add_f32_e32 v48, 0x41900000, v225
	v_fma_f32 v48, v224, |v48|, v58
	v_exp_f32_e32 v236, v48
	v_add_f32_e32 v48, 0x41980000, v225
	v_fma_f32 v48, v224, |v48|, v59
	v_exp_f32_e32 v237, v48
	v_add_f32_e32 v48, 0x41c00000, v225
	v_fma_f32 v48, v224, |v48|, v60
	v_exp_f32_e32 v60, v48
	v_add_f32_e32 v48, 0x41c80000, v225
	v_fma_f32 v48, v224, |v48|, v61
	v_exp_f32_e32 v61, v48
	v_add_f32_e32 v48, 0x41d00000, v225
	v_fma_f32 v52, v224, |v48|, v62
	ds_read_b64_tr_b16 v[48:49], v204 offset:55296
	ds_read_b64_tr_b16 v[50:51], v204 offset:56832
	ds_read_b64_tr_b16 v[58:59], v204 offset:56896
	ds_read_b64_tr_b16 v[56:57], v204 offset:55360
	v_exp_f32_e32 v62, v52
	v_add_f32_e32 v239, 0x41d80000, v225
	v_cvt_pk_bf16_f32 v52, v226, v227
	v_cvt_pk_bf16_f32 v53, v228, v229
	v_cvt_pk_bf16_f32 v54, v230, v231
	v_cvt_pk_bf16_f32 v55, v232, v55
	s_waitcnt lgkmcnt(2)
; #define LAS __attribute__((address_space(3)))
; __device__ __forceinline__ unsigned pk2(float lo, float hi) { f32x2_t v = {lo, hi}; bf16x2_t b = __builtin_convertvector(v, bf16x2_t); return __builtin_bit_cast(unsigned, b); }
; __device__ __forceinline__ s16x4 trrd(LAS const unsigned char* p) { return __builtin_bit_cast(s16x4, __builtin_amdgcn_ds_read_tr16_b64_v4i16((LAS v4i16_t*)p)); }
; __device__ __forceinline__ float attn_tile_exp(f32x16& st, int j, float tlf, float bsl, float rlo, float rhi) {
;     float sum = 0.f;
; #pragma unroll
;     for (int i = 0; i < 16; ++i) { const float tmp = (float)(32 * j - 64 + (i & 3) + 8 * (i >> 2)) + tlf;
;         float arg = __builtin_fmaf(-bsl, __builtin_fabsf(tmp), st[i]);
;         arg = (tmp >= rlo && tmp <= rhi) ? arg : -1.0e30f;
;         const float pe = __builtin_amdgcn_exp2f(arg); st[i] = pe; sum += pe; }
;     return sum;
; template <bool FUSED> __device__ __forceinline__ void attn_phase(const Args& a, LAS unsigned char* lds, int tid, int lane, int wave) {
;     ...
;         for (int j = 0; j < 5; ++j) {
;             f32x16 st;
; #pragma unroll
;             for (int i = 0; i < 16; ++i) st[i] = -mb;
;             LAS const unsigned char* kp = lds + (32 * wave + 32 * j + l31) * KP + 16 * h;
; #pragma unroll
;             for (int ks = 0; ks < 4; ++ks) { const bf16x8 kf = *(LAS const bf16x8*)(kp + 32 * ks); st = __builtin_amdgcn_mfma_f32_32x32x16_bf16(kf, qf[ks], st, 0, 0, 0); }
;             sum += attn_tile_exp(st, j, tlf, bsl, rlo, rhi);
; #pragma unroll
;             for (int s2 = 0; s2 < 2; ++s2) { u32x4 pw; pw.x = pk2(st[8 * s2 + 0], st[8 * s2 + 1]); pw.y = pk2(st[8 * s2 + 2], st[8 * s2 + 3]); pw.z = pk2(st[8 * s2 + 4], st[8 * s2 + 5]); pw.w = pk2(st[8 * s2 + 6], st[8 * s2 + 7]);
;                 const bf16x8 pf = __builtin_bit_cast(bf16x8, pw);
;                 LAS const unsigned char* vp = lds + LDS_VOFF + (32 * wave + 32 * j + 16 * s2 + 4 * h + q) * VP + 32 * blk + 8 * p;
; #pragma unroll
;                 for (int dt = 0; dt < 2; ++dt) { const s16x4 lo = trrd(vp + dt * 64), hi = trrd(vp + 8 * VP + dt * 64);
;                     const bf16x8 vf = __builtin_shufflevector(lo, hi, 0, 1, 2, 3, 4, 5, 6, 7);
;                     o[dt] = __builtin_amdgcn_mfma_f32_32x32x16_bf16(vf, pf, o[dt], 0, 0, 0); } }
;             __builtin_amdgcn_sched_barrier(0);
;         }
	s_nop 0
	v_mfma_f32_32x32x16_bf16 v[32:47], v[48:51], v[52:55], v[32:47]
	v_fma_f32 v63, v224, |v239|, v63
	ds_read_b64_tr_b16 v[48:49], v204 offset:58368
	ds_read_b64_tr_b16 v[50:51], v204 offset:59904
	v_exp_f32_e32 v63, v63
	s_waitcnt lgkmcnt(2)
	v_mfma_f32_32x32x16_bf16 v[16:31], v[56:59], v[52:55], v[16:31]
	ds_read_b64_tr_b16 v[58:59], v204 offset:59968
	ds_read_b64_tr_b16 v[56:57], v204 offset:58432
	v_cvt_pk_bf16_f32 v52, v233, v235
	v_cvt_pk_bf16_f32 v53, v236, v237
	v_cvt_pk_bf16_f32 v54, v60, v61
	v_cvt_pk_bf16_f32 v55, v62, v63
	s_waitcnt lgkmcnt(2)
	s_nop 0
	v_mfma_f32_32x32x16_bf16 v[32:47], v[48:51], v[52:55], v[32:47]
	v_add_f32_e32 v48, v235, v234
	v_add_f32_e32 v48, v236, v48
	v_add_f32_e32 v48, v237, v48
	v_add_f32_e32 v48, v60, v48
	v_add_f32_e32 v48, v61, v48
	v_add_f32_e32 v48, v62, v48
	v_add_f32_e32 v48, v63, v48
	s_waitcnt lgkmcnt(0)
	v_mfma_f32_32x32x16_bf16 v[16:31], v[56:59], v[52:55], v[16:31]
	v_add_f32_e32 v238, v238, v48
	ds_read_b128 v[226:229], v205
	ds_read_b128 v[230:233], v205 offset:32
	v_add_f32_e32 v239, 0x42000000, v225
	v_add_f32_e32 v240, 0x42040000, v225
	s_waitcnt lgkmcnt(1)
	v_mfma_f32_32x32x16_bf16 v[48:63], v[226:229], v[136:139], v[0:15]
	ds_read_b128 v[226:229], v205 offset:64
	ds_read_b128 v[234:237], v205 offset:96
	v_add_f32_e32 v241, 0x42080000, v225
	v_add_f32_e32 v242, 0x420c0000, v225
	s_waitcnt lgkmcnt(2)
	v_mfma_f32_32x32x16_bf16 v[48:63], v[230:233], v[132:135], v[48:63]
	v_add_f32_e32 v230, 0x42200000, v225
	v_add_f32_e32 v231, 0x42240000, v225
	s_waitcnt lgkmcnt(1)
	v_mfma_f32_32x32x16_bf16 v[48:63], v[226:229], v[128:131], v[48:63]
	s_waitcnt lgkmcnt(0)
	v_mfma_f32_32x32x16_bf16 v[48:63], v[234:237], v[140:143], v[48:63]
	s_nop 11
	v_fma_f32 v48, v224, |v239|, v48
	v_fma_f32 v49, v224, |v240|, v49
	v_fma_f32 v50, v224, |v241|, v50
	v_fma_f32 v51, v224, |v242|, v51
	v_fma_f32 v52, v224, |v230|, v52
	v_fma_f32 v53, v224, |v231|, v53
	v_exp_f32_e32 v227, v49
	v_mov_b32_e32 v49, v53
	v_exp_f32_e32 v231, v49
	v_add_f32_e32 v49, 0x42280000, v225
	v_exp_f32_e32 v228, v50
	v_fma_f32 v49, v224, |v49|, v54
	v_exp_f32_e32 v226, v48
	v_exp_f32_e32 v232, v49
	v_add_f32_e32 v49, 0x422c0000, v225
	v_fma_f32 v49, v224, |v49|, v55
	v_exp_f32_e32 v229, v51
	v_exp_f32_e32 v230, v52
	v_add_f32_e32 v48, 0, v226
	v_exp_f32_e32 v55, v49
	v_add_f32_e32 v49, 0x42400000, v225
	v_add_f32_e32 v48, v227, v48
	v_add_f32_e32 v48, v228, v48
	v_fma_f32 v49, v224, |v49|, v56
	v_add_f32_e32 v48, v229, v48
	v_add_f32_e32 v48, v230, v48
	v_exp_f32_e32 v233, v49
	v_add_f32_e32 v48, v231, v48
	v_add_f32_e32 v48, v232, v48
	v_add_f32_e32 v48, v55, v48
	v_add_f32_e32 v234, v233, v48
	v_add_f32_e32 v48, 0x42440000, v225
	v_fma_f32 v48, v224, |v48|, v57
	v_exp_f32_e32 v235, v48
	v_add_f32_e32 v48, 0x42480000, v225
	v_fma_f32 v48, v224, |v48|, v58
	v_exp_f32_e32 v236, v48
	v_add_f32_e32 v48, 0x424c0000, v225
	v_fma_f32 v48, v224, |v48|, v59
	v_exp_f32_e32 v237, v48
	v_add_f32_e32 v48, 0x42600000, v225
	v_fma_f32 v48, v224, |v48|, v60
	v_exp_f32_e32 v60, v48
	v_add_f32_e32 v48, 0x42640000, v225
	v_fma_f32 v48, v224, |v48|, v61
	v_exp_f32_e32 v61, v48
	v_add_f32_e32 v48, 0x42680000, v225
	v_fma_f32 v52, v224, |v48|, v62
	ds_read_b64_tr_b16 v[48:49], v206 offset:55296
	ds_read_b64_tr_b16 v[50:51], v206 offset:56832
	ds_read_b64_tr_b16 v[58:59], v206 offset:56896
	ds_read_b64_tr_b16 v[56:57], v206 offset:55360
	v_exp_f32_e32 v62, v52
	v_add_f32_e32 v239, 0x426c0000, v225
	v_cvt_pk_bf16_f32 v52, v226, v227
	v_cvt_pk_bf16_f32 v53, v228, v229
	v_cvt_pk_bf16_f32 v54, v230, v231
	v_cvt_pk_bf16_f32 v55, v232, v55
	s_waitcnt lgkmcnt(2)
	s_nop 0
	v_mfma_f32_32x32x16_bf16 v[32:47], v[48:51], v[52:55], v[32:47]
	v_fma_f32 v63, v224, |v239|, v63
	ds_read_b64_tr_b16 v[48:49], v206 offset:58368
	ds_read_b64_tr_b16 v[50:51], v206 offset:59904
	v_exp_f32_e32 v63, v63
	s_waitcnt lgkmcnt(2)
	v_mfma_f32_32x32x16_bf16 v[16:31], v[56:59], v[52:55], v[16:31]
	ds_read_b64_tr_b16 v[58:59], v206 offset:59968
	ds_read_b64_tr_b16 v[56:57], v206 offset:58432
	v_cvt_pk_bf16_f32 v52, v233, v235
	v_cvt_pk_bf16_f32 v53, v236, v237
	v_cvt_pk_bf16_f32 v54, v60, v61
	v_cvt_pk_bf16_f32 v55, v62, v63
	s_waitcnt lgkmcnt(2)
	s_nop 0
	v_mfma_f32_32x32x16_bf16 v[32:47], v[48:51], v[52:55], v[32:47]
	v_add_f32_e32 v48, v235, v234
	v_add_f32_e32 v48, v236, v48
	v_add_f32_e32 v48, v237, v48
	v_add_f32_e32 v48, v60, v48
	v_add_f32_e32 v48, v61, v48
	v_add_f32_e32 v48, v62, v48
	v_add_f32_e32 v48, v63, v48
	s_waitcnt lgkmcnt(0)
	v_mfma_f32_32x32x16_bf16 v[16:31], v[56:59], v[52:55], v[16:31]
	v_add_f32_e32 v60, v238, v48
	s_branch .Lattn1_t4

; #define LAS __attribute__((address_space(3)))
; __global__ void __launch_bounds__(512, 2) mega_fwd(Args a) {
;     extern __shared__ __attribute__((aligned(16))) unsigned char lds_raw[];
;     LAS unsigned char* lds = (LAS unsigned char*)lds_raw;
;     cg::grid_group grid = cg::this_grid();
;     const int tid = threadIdx.x, lane = tid & 63, wave = __builtin_amdgcn_readfirstlane(tid >> 6);
	.amdhsa_kernel _Z8mega_fwd4Args
		.amdhsa_group_segment_fixed_size 0
		.amdhsa_private_segment_fixed_size 0
		.amdhsa_kernarg_size 328
		.amdhsa_user_sgpr_count 2
		.amdhsa_user_sgpr_dispatch_ptr 0
		.amdhsa_user_sgpr_queue_ptr 0
		.amdhsa_user_sgpr_kernarg_segment_ptr 1
		.amdhsa_user_sgpr_dispatch_id 0
		.amdhsa_user_sgpr_kernarg_preload_length 0
		.amdhsa_user_sgpr_kernarg_preload_offset 0
		.amdhsa_user_sgpr_private_segment_size 0
		.amdhsa_uses_dynamic_stack 0
		.amdhsa_enable_private_segment 0
		.amdhsa_system_sgpr_workgroup_id_x 1
		.amdhsa_system_sgpr_workgroup_id_y 0
		.amdhsa_system_sgpr_workgroup_id_z 0
		.amdhsa_system_sgpr_workgroup_info 0
		.amdhsa_system_vgpr_workitem_id 2
		.amdhsa_next_free_vgpr 256
		.amdhsa_next_free_sgpr 102
		.amdhsa_accum_offset 256
		.amdhsa_reserve_vcc 1
		.amdhsa_float_round_mode_32 0
		.amdhsa_float_round_mode_16_64 0
		.amdhsa_float_denorm_mode_32 3
		.amdhsa_float_denorm_mode_16_64 3
		.amdhsa_dx10_clamp 1
		.amdhsa_ieee_mode 1
		.amdhsa_fp16_overflow 0
		.amdhsa_tg_split 0
		.amdhsa_exception_fp_ieee_invalid_op 0
		.amdhsa_exception_fp_denorm_src 0
		.amdhsa_exception_fp_ieee_div_zero 0
		.amdhsa_exception_fp_ieee_overflow 0
		.amdhsa_exception_fp_ieee_underflow 0
		.amdhsa_exception_fp_ieee_inexact 0
		.amdhsa_exception_int_div_zero 0
	.end_amdhsa_kernel

; #define LAS __attribute__((address_space(3)))
; __global__ void __launch_bounds__(512, 2) mega_fwd(Args a) {
;     extern __shared__ __attribute__((aligned(16))) unsigned char lds_raw[];
;     LAS unsigned char* lds = (LAS unsigned char*)lds_raw;
;     cg::grid_group grid = cg::this_grid();
;     const int tid = threadIdx.x, lane = tid & 63, wave = __builtin_amdgcn_readfirstlane(tid >> 6);
amdhsa.kernels:
  - .agpr_count:     0
    .args:
      - .offset:         0
        .size:           72
        .value_kind:     by_value
      - .offset:         72
        .size:           4
        .value_kind:     hidden_block_count_x
      - .offset:         76
        .size:           4
        .value_kind:     hidden_block_count_y
      - .offset:         80
        .size:           4
        .value_kind:     hidden_block_count_z
      - .offset:         84
        .size:           2
        .value_kind:     hidden_group_size_x
      - .offset:         86
        .size:           2
        .value_kind:     hidden_group_size_y
      - .offset:         88
        .size:           2
        .value_kind:     hidden_group_size_z
      - .offset:         90
        .size:           2
        .value_kind:     hidden_remainder_x
      - .offset:         92
        .size:           2
        .value_kind:     hidden_remainder_y
      - .offset:         94
        .size:           2
        .value_kind:     hidden_remainder_z
      - .offset:         112
        .size:           8
        .value_kind:     hidden_global_offset_x
      - .offset:         120
        .size:           8
        .value_kind:     hidden_global_offset_y
      - .offset:         128
        .size:           8
        .value_kind:     hidden_global_offset_z
      - .offset:         136
        .size:           2
        .value_kind:     hidden_grid_dims
      - .offset:         160
        .size:           8
        .value_kind:     hidden_multigrid_sync_arg
      - .offset:         192
        .size:           4
        .value_kind:     hidden_dynamic_lds_size
    .group_segment_fixed_size: 0
    .kernarg_segment_align: 8
    .kernarg_segment_size: 328
    .language:       OpenCL C
    .language_version:
      - 2
      - 0
    .max_flat_workgroup_size: 512
    .name:           _Z8mega_fwd4Args
    .private_segment_fixed_size: 0
    .sgpr_count:     108
    .sgpr_spill_count: 0
    .symbol:         _Z8mega_fwd4Args.kd
    .uniform_work_group_size: 1
    .uses_dynamic_stack: false
    .vgpr_count:     256
    .vgpr_spill_count: 0
    .wavefront_size: 64
